# strategy 7.4 applied to p3a S4: s_setprio 1 for waves 4-7 for the duration of the triangular inverse, so the two waves of a SIMD run out of phase and one wave's f32 MFMA chain overlaps the other's VAL
# speedup vs baseline: 1.0155x; 1.0084x over previous
.LBB0_653:
	v_readlane_b32 s1, v249, 49
	s_nop 0
	s_cmp_ge_u32 s1, 4
	s_cbranch_scc0 .Ls4_noprio
	s_setprio 1
.Ls4_noprio:
	v_readlane_b32 s0, v248, 20
	v_readlane_b32 s4, v248, 2
	v_readlane_b32 s5, v248, 17
	s_lshl_b32 s0, s0, 3
	s_add_i32 s0, s0, s1
	s_add_i32 s72, s72, s0
	s_lshr_b32 s1, s72, 4
	s_mov_b32 s3, 0x24300000
	s_cmp_eq_u32 s1, 2
	s_cselect_b32 s2, s3, 0x26000000
	s_cmp_lg_u32 s1, 1
	s_cselect_b32 s1, s2, 0x1d000000
	s_cmp_gt_u32 s72, 15
	s_cselect_b32 s1, s1, 0x1ed00000
	s_add_u32 s1, s70, s1
	s_addc_u32 s2, s71, 0
	s_lshl_b32 s0, s0, 6
	s_and_b32 s0, s0, 0x3c0
	s_add_i32 s0, s0, s85
	s_mul_hi_i32 s3, s0, 0x7400
	s_mulk_i32 s0, 0x7400
	s_add_u32 s6, s1, s0
	s_addc_u32 s7, s2, s3
	v_and_b32_e32 v20, 15, v1
	v_lshl_add_u32 v138, v20, 2, s4
	v_or_b32_e32 v139, 32, v1
	v_cmp_lt_u32_e64 s[2:3], 31, v1
	v_and_b32_e32 v154, 31, v1
	v_add_u32_e32 v154, 1, v154
	v_lshrrev_b32_e32 v155, 2, v154
	v_and_b32_e32 v154, 3, v154
	v_lshlrev_b32_e32 v20, 3, v155
	v_sub_u32_e32 v20, 0x104, v20
	v_mul_u32_u24_e32 v20, v155, v20
	v_lshlrev_b32_e32 v21, 2, v155
	v_sub_u32_e32 v21, 64, v21
	v_mul_u32_u24_e32 v21, v154, v21
	v_add_u32_e32 v20, v20, v21
	v_lshrrev_b32_e32 v21, 5, v1
	v_add_u32_e32 v20, v20, v21
	v_subrev_u32_e32 v20, 32, v20
	v_lshl_add_u32 v152, v20, 2, s4
	v_subrev_u32_e32 v153, 36, v1
	v_cndmask_b32_e64 v153, v1, v153, s[2:3]
	ds_read_b32 v226, v152 offset:0
	ds_read_b32 v227, v152 offset:8
	ds_read_b32 v228, v152 offset:16
	ds_read_b32 v229, v152 offset:24
	ds_read_b32 v230, v152 offset:32
	ds_read_b32 v231, v152 offset:40
	ds_read_b32 v232, v152 offset:48
	ds_read_b32 v233, v152 offset:56
	ds_read_b32 v234, v152 offset:64
	ds_read_b32 v235, v152 offset:72
	ds_read_b32 v236, v152 offset:80
	ds_read_b32 v237, v152 offset:88
	ds_read_b32 v238, v152 offset:96
	ds_read_b32 v239, v152 offset:104
	ds_read_b32 v240, v152 offset:112
	ds_read_b32 v241, v152 offset:120
	ds_read_b32 v148, v138 offset:8432
	v_cmp_eq_u32_e32 vcc, 63, v139
	s_nop 1
	v_cndmask_b32_e64 v134, 0, 1.0, vcc
	ds_read_b32 v144, v138 offset:8416
	s_waitcnt lgkmcnt(2)
	v_cmp_eq_u32_e32 vcc, 62, v139
	s_nop 1
	v_cndmask_b32_e64 v130, 0, 1.0, vcc
	v_mov_b32_e32 v129, v134
	ds_read_b32 v140, v138 offset:8400
	s_waitcnt lgkmcnt(2)
	v_cmp_eq_u32_e32 vcc, 61, v139
	v_mul_f32_dpp v133, -v148, v129 row_newbcast:3 row_mask:0xf bank_mask:0xf
	s_nop 0
	v_cndmask_b32_e64 v134, 0, 1.0, vcc
	v_add_f32_e32 v128, v130, v133
	ds_read_b32 v148, v138 offset:8384
	s_waitcnt lgkmcnt(2)
	v_cmp_eq_u32_e32 vcc, 60, v139
	v_mul_f32_dpp v137, -v144, v129 row_newbcast:3 row_mask:0xf bank_mask:0xf
	v_mul_f32_dpp v136, -v144, v128 row_newbcast:2 row_mask:0xf bank_mask:0xf
	v_cndmask_b32_e64 v130, 0, 1.0, vcc
	v_add_f32_e32 v21, v136, v137
	v_add_f32_e32 v127, v134, v21
	ds_read_b32 v144, v138 offset:8352
	s_waitcnt lgkmcnt(2)
	v_cmp_eq_u32_e32 vcc, 59, v139
	v_mul_f32_dpp v132, -v140, v128 row_newbcast:2 row_mask:0xf bank_mask:0xf
	v_mul_f32_dpp v133, -v140, v129 row_newbcast:3 row_mask:0xf bank_mask:0xf
	v_mul_f32_dpp v131, -v140, v127 row_newbcast:1 row_mask:0xf bank_mask:0xf
	v_cndmask_b32_e64 v134, 0, 1.0, vcc
	v_add_f32_e32 v20, v130, v131
	v_add_f32_e32 v21, v132, v133
	v_add_f32_e32 v126, v20, v21
	ds_read_b32 v140, v138 offset:8320
	s_waitcnt lgkmcnt(2)
	v_cmp_eq_u32_e32 vcc, 58, v139
	v_mul_f32_dpp v135, -v148, v127 row_newbcast:1 row_mask:0xf bank_mask:0xf
	v_mul_f32_dpp v136, -v148, v128 row_newbcast:2 row_mask:0xf bank_mask:0xf
	v_mul_f32_dpp v137, -v148, v129 row_newbcast:3 row_mask:0xf bank_mask:0xf
	v_fmac_f32_dpp v134, -v148, v126 row_newbcast:0 row_mask:0xf bank_mask:0xf
	v_cndmask_b32_e64 v130, 0, 1.0, vcc
	v_add_f32_e32 v20, v134, v135
	v_add_f32_e32 v21, v136, v137
	v_add_f32_e32 v125, v20, v21
	ds_read_b32 v148, v138 offset:8288
	s_waitcnt lgkmcnt(2)
	v_cmp_eq_u32_e32 vcc, 57, v139
	v_fmac_f32_dpp v130, -v144, v126 row_newbcast:4 row_mask:0xf bank_mask:0xf
	v_mul_f32_dpp v131, -v144, v127 row_newbcast:5 row_mask:0xf bank_mask:0xf
	v_mul_f32_dpp v132, -v144, v128 row_newbcast:6 row_mask:0xf bank_mask:0xf
	v_mul_f32_dpp v133, -v144, v125 row_newbcast:3 row_mask:0xf bank_mask:0xf
	s_nop 1
	v_fmac_f32_dpp v133, -v144, v129 row_newbcast:7 row_mask:0xf bank_mask:0xf
	v_cndmask_b32_e64 v134, 0, 1.0, vcc
	v_add_f32_e32 v20, v130, v131
	v_add_f32_e32 v21, v132, v133
	v_add_f32_e32 v124, v20, v21
	ds_read_b32 v144, v138 offset:8256
	s_waitcnt lgkmcnt(2)
	v_cmp_eq_u32_e32 vcc, 56, v139
	v_mul_f32_dpp v137, -v140, v125 row_newbcast:3 row_mask:0xf bank_mask:0xf
	v_fmac_f32_dpp v134, -v140, v126 row_newbcast:4 row_mask:0xf bank_mask:0xf
	v_mul_f32_dpp v135, -v140, v127 row_newbcast:5 row_mask:0xf bank_mask:0xf
	v_mul_f32_dpp v136, -v140, v124 row_newbcast:2 row_mask:0xf bank_mask:0xf
	v_fmac_f32_dpp v137, -v140, v129 row_newbcast:7 row_mask:0xf bank_mask:0xf
	s_nop 0
	v_fmac_f32_dpp v136, -v140, v128 row_newbcast:6 row_mask:0xf bank_mask:0xf
	v_cndmask_b32_e64 v130, 0, 1.0, vcc
	v_add_f32_e32 v20, v134, v135
	v_add_f32_e32 v21, v136, v137
	v_add_f32_e32 v123, v20, v21
	ds_read_b32 v140, v138 offset:8208
	s_waitcnt lgkmcnt(2)
	v_cmp_eq_u32_e32 vcc, 55, v139
	v_mul_f32_dpp v132, -v148, v124 row_newbcast:2 row_mask:0xf bank_mask:0xf
	v_mul_f32_dpp v133, -v148, v125 row_newbcast:3 row_mask:0xf bank_mask:0xf
	v_fmac_f32_dpp v130, -v148, v126 row_newbcast:4 row_mask:0xf bank_mask:0xf
	v_mul_f32_dpp v131, -v148, v123 row_newbcast:1 row_mask:0xf bank_mask:0xf
	v_fmac_f32_dpp v132, -v148, v128 row_newbcast:6 row_mask:0xf bank_mask:0xf
	v_fmac_f32_dpp v133, -v148, v129 row_newbcast:7 row_mask:0xf bank_mask:0xf
	v_fmac_f32_dpp v131, -v148, v127 row_newbcast:5 row_mask:0xf bank_mask:0xf
	v_cndmask_b32_e64 v134, 0, 1.0, vcc
	v_add_f32_e32 v20, v130, v131
	v_add_f32_e32 v21, v132, v133
	v_add_f32_e32 v122, v20, v21
	ds_read_b32 v148, v138 offset:8160
	s_waitcnt lgkmcnt(2)
	v_cmp_eq_u32_e32 vcc, 54, v139
	v_mul_f32_dpp v135, -v144, v123 row_newbcast:1 row_mask:0xf bank_mask:0xf
	v_mul_f32_dpp v136, -v144, v124 row_newbcast:2 row_mask:0xf bank_mask:0xf
	v_mul_f32_dpp v137, -v144, v125 row_newbcast:3 row_mask:0xf bank_mask:0xf
	v_fmac_f32_dpp v134, -v144, v122 row_newbcast:0 row_mask:0xf bank_mask:0xf
	v_fmac_f32_dpp v135, -v144, v127 row_newbcast:5 row_mask:0xf bank_mask:0xf
	v_fmac_f32_dpp v136, -v144, v128 row_newbcast:6 row_mask:0xf bank_mask:0xf
	v_fmac_f32_dpp v137, -v144, v129 row_newbcast:7 row_mask:0xf bank_mask:0xf
	v_fmac_f32_dpp v134, -v144, v126 row_newbcast:4 row_mask:0xf bank_mask:0xf
	v_cndmask_b32_e64 v130, 0, 1.0, vcc
	v_add_f32_e32 v20, v134, v135
	v_add_f32_e32 v21, v136, v137
	v_add_f32_e32 v121, v20, v21
	ds_read_b32 v144, v138 offset:8112
	s_waitcnt lgkmcnt(2)
	v_cmp_eq_u32_e32 vcc, 53, v139
	v_fmac_f32_dpp v130, -v140, v122 row_newbcast:4 row_mask:0xf bank_mask:0xf
	v_mul_f32_dpp v131, -v140, v123 row_newbcast:5 row_mask:0xf bank_mask:0xf
	v_mul_f32_dpp v132, -v140, v124 row_newbcast:6 row_mask:0xf bank_mask:0xf
	v_mul_f32_dpp v133, -v140, v121 row_newbcast:3 row_mask:0xf bank_mask:0xf
	v_fmac_f32_dpp v130, -v140, v126 row_newbcast:8 row_mask:0xf bank_mask:0xf
	v_fmac_f32_dpp v131, -v140, v127 row_newbcast:9 row_mask:0xf bank_mask:0xf
	v_fmac_f32_dpp v132, -v140, v128 row_newbcast:10 row_mask:0xf bank_mask:0xf
	v_fmac_f32_dpp v133, -v140, v125 row_newbcast:7 row_mask:0xf bank_mask:0xf
	s_nop 1
	v_fmac_f32_dpp v133, -v140, v129 row_newbcast:11 row_mask:0xf bank_mask:0xf
	v_cndmask_b32_e64 v134, 0, 1.0, vcc
	v_add_f32_e32 v20, v130, v131
	v_add_f32_e32 v21, v132, v133
	v_add_f32_e32 v120, v20, v21
	ds_read_b32 v140, v138 offset:8064
	s_waitcnt lgkmcnt(2)
	v_cmp_eq_u32_e32 vcc, 52, v139
	v_mul_f32_dpp v137, -v148, v121 row_newbcast:3 row_mask:0xf bank_mask:0xf
	v_fmac_f32_dpp v134, -v148, v122 row_newbcast:4 row_mask:0xf bank_mask:0xf
	v_mul_f32_dpp v135, -v148, v123 row_newbcast:5 row_mask:0xf bank_mask:0xf
	v_mul_f32_dpp v136, -v148, v120 row_newbcast:2 row_mask:0xf bank_mask:0xf
	v_fmac_f32_dpp v137, -v148, v125 row_newbcast:7 row_mask:0xf bank_mask:0xf
	v_fmac_f32_dpp v134, -v148, v126 row_newbcast:8 row_mask:0xf bank_mask:0xf
	v_fmac_f32_dpp v135, -v148, v127 row_newbcast:9 row_mask:0xf bank_mask:0xf
	v_fmac_f32_dpp v136, -v148, v124 row_newbcast:6 row_mask:0xf bank_mask:0xf
	v_fmac_f32_dpp v137, -v148, v129 row_newbcast:11 row_mask:0xf bank_mask:0xf
	s_nop 0
	v_fmac_f32_dpp v136, -v148, v128 row_newbcast:10 row_mask:0xf bank_mask:0xf
	v_cndmask_b32_e64 v130, 0, 1.0, vcc
	v_add_f32_e32 v20, v134, v135
	v_add_f32_e32 v21, v136, v137
	v_add_f32_e32 v119, v20, v21
	ds_read_b32 v148, v138 offset:8000
	s_waitcnt lgkmcnt(2)
	v_cmp_eq_u32_e32 vcc, 51, v139
	v_mul_f32_dpp v132, -v144, v120 row_newbcast:2 row_mask:0xf bank_mask:0xf
	v_mul_f32_dpp v133, -v144, v121 row_newbcast:3 row_mask:0xf bank_mask:0xf
	v_fmac_f32_dpp v130, -v144, v122 row_newbcast:4 row_mask:0xf bank_mask:0xf
	v_mul_f32_dpp v131, -v144, v119 row_newbcast:1 row_mask:0xf bank_mask:0xf
	v_fmac_f32_dpp v132, -v144, v124 row_newbcast:6 row_mask:0xf bank_mask:0xf
	v_fmac_f32_dpp v133, -v144, v125 row_newbcast:7 row_mask:0xf bank_mask:0xf
	v_fmac_f32_dpp v130, -v144, v126 row_newbcast:8 row_mask:0xf bank_mask:0xf
	v_fmac_f32_dpp v131, -v144, v123 row_newbcast:5 row_mask:0xf bank_mask:0xf
	v_fmac_f32_dpp v132, -v144, v128 row_newbcast:10 row_mask:0xf bank_mask:0xf
	v_fmac_f32_dpp v133, -v144, v129 row_newbcast:11 row_mask:0xf bank_mask:0xf
	v_fmac_f32_dpp v131, -v144, v127 row_newbcast:9 row_mask:0xf bank_mask:0xf
	v_cndmask_b32_e64 v134, 0, 1.0, vcc
	v_add_f32_e32 v20, v130, v131
	v_add_f32_e32 v21, v132, v133
	v_add_f32_e32 v118, v20, v21
	ds_read_b32 v144, v138 offset:7936
	s_waitcnt lgkmcnt(2)
	v_cmp_eq_u32_e32 vcc, 50, v139
	v_mul_f32_dpp v135, -v140, v119 row_newbcast:1 row_mask:0xf bank_mask:0xf
	v_mul_f32_dpp v136, -v140, v120 row_newbcast:2 row_mask:0xf bank_mask:0xf
	v_mul_f32_dpp v137, -v140, v121 row_newbcast:3 row_mask:0xf bank_mask:0xf
	v_fmac_f32_dpp v134, -v140, v118 row_newbcast:0 row_mask:0xf bank_mask:0xf
	v_fmac_f32_dpp v135, -v140, v123 row_newbcast:5 row_mask:0xf bank_mask:0xf
	v_fmac_f32_dpp v136, -v140, v124 row_newbcast:6 row_mask:0xf bank_mask:0xf
	v_fmac_f32_dpp v137, -v140, v125 row_newbcast:7 row_mask:0xf bank_mask:0xf
	v_fmac_f32_dpp v134, -v140, v122 row_newbcast:4 row_mask:0xf bank_mask:0xf
	v_fmac_f32_dpp v135, -v140, v127 row_newbcast:9 row_mask:0xf bank_mask:0xf
	v_fmac_f32_dpp v136, -v140, v128 row_newbcast:10 row_mask:0xf bank_mask:0xf
	v_fmac_f32_dpp v137, -v140, v129 row_newbcast:11 row_mask:0xf bank_mask:0xf
	v_fmac_f32_dpp v134, -v140, v126 row_newbcast:8 row_mask:0xf bank_mask:0xf
	v_cndmask_b32_e64 v130, 0, 1.0, vcc
	v_add_f32_e32 v20, v134, v135
	v_add_f32_e32 v21, v136, v137
	v_add_f32_e32 v117, v20, v21
	ds_read_b32 v140, v138 offset:7872
	s_waitcnt lgkmcnt(2)
	v_cmp_eq_u32_e32 vcc, 49, v139
	v_fmac_f32_dpp v130, -v148, v118 row_newbcast:4 row_mask:0xf bank_mask:0xf
	v_mul_f32_dpp v131, -v148, v119 row_newbcast:5 row_mask:0xf bank_mask:0xf
	v_mul_f32_dpp v132, -v148, v120 row_newbcast:6 row_mask:0xf bank_mask:0xf
	v_mul_f32_dpp v133, -v148, v117 row_newbcast:3 row_mask:0xf bank_mask:0xf
	v_fmac_f32_dpp v130, -v148, v122 row_newbcast:8 row_mask:0xf bank_mask:0xf
	v_fmac_f32_dpp v131, -v148, v123 row_newbcast:9 row_mask:0xf bank_mask:0xf
	v_fmac_f32_dpp v132, -v148, v124 row_newbcast:10 row_mask:0xf bank_mask:0xf
	v_fmac_f32_dpp v133, -v148, v121 row_newbcast:7 row_mask:0xf bank_mask:0xf
	v_fmac_f32_dpp v130, -v148, v126 row_newbcast:12 row_mask:0xf bank_mask:0xf
	v_fmac_f32_dpp v131, -v148, v127 row_newbcast:13 row_mask:0xf bank_mask:0xf
	v_fmac_f32_dpp v132, -v148, v128 row_newbcast:14 row_mask:0xf bank_mask:0xf
	v_fmac_f32_dpp v133, -v148, v125 row_newbcast:11 row_mask:0xf bank_mask:0xf
	s_nop 1
	v_fmac_f32_dpp v133, -v148, v129 row_newbcast:15 row_mask:0xf bank_mask:0xf
	v_cndmask_b32_e64 v134, 0, 1.0, vcc
	v_add_f32_e32 v20, v130, v131
	v_add_f32_e32 v21, v132, v133
	v_add_f32_e32 v116, v20, v21
	ds_read_b32 v148, v138 offset:7808
	s_waitcnt lgkmcnt(2)
	v_cmp_eq_u32_e32 vcc, 48, v139
	v_mul_f32_dpp v137, -v144, v117 row_newbcast:3 row_mask:0xf bank_mask:0xf
	v_fmac_f32_dpp v134, -v144, v118 row_newbcast:4 row_mask:0xf bank_mask:0xf
	v_mul_f32_dpp v135, -v144, v119 row_newbcast:5 row_mask:0xf bank_mask:0xf
	v_mul_f32_dpp v136, -v144, v116 row_newbcast:2 row_mask:0xf bank_mask:0xf
	v_fmac_f32_dpp v137, -v144, v121 row_newbcast:7 row_mask:0xf bank_mask:0xf
	v_fmac_f32_dpp v134, -v144, v122 row_newbcast:8 row_mask:0xf bank_mask:0xf
	v_fmac_f32_dpp v135, -v144, v123 row_newbcast:9 row_mask:0xf bank_mask:0xf
	v_fmac_f32_dpp v136, -v144, v120 row_newbcast:6 row_mask:0xf bank_mask:0xf
	v_fmac_f32_dpp v137, -v144, v125 row_newbcast:11 row_mask:0xf bank_mask:0xf
	v_fmac_f32_dpp v134, -v144, v126 row_newbcast:12 row_mask:0xf bank_mask:0xf
	v_fmac_f32_dpp v135, -v144, v127 row_newbcast:13 row_mask:0xf bank_mask:0xf
	v_fmac_f32_dpp v136, -v144, v124 row_newbcast:10 row_mask:0xf bank_mask:0xf
	v_fmac_f32_dpp v137, -v144, v129 row_newbcast:15 row_mask:0xf bank_mask:0xf
	s_nop 0
	v_fmac_f32_dpp v136, -v144, v128 row_newbcast:14 row_mask:0xf bank_mask:0xf
	v_cndmask_b32_e64 v130, 0, 1.0, vcc
	v_add_f32_e32 v20, v134, v135
	v_add_f32_e32 v21, v136, v137
	v_add_f32_e32 v115, v20, v21
	ds_read_b32 v144, v138 offset:7728
	ds_read_b32 v145, v138 offset:7792
	s_waitcnt lgkmcnt(3)
	v_cmp_eq_u32_e32 vcc, 47, v139
	v_mul_f32_dpp v132, -v140, v116 row_newbcast:2 row_mask:0xf bank_mask:0xf
	v_mul_f32_dpp v133, -v140, v117 row_newbcast:3 row_mask:0xf bank_mask:0xf
	v_fmac_f32_dpp v130, -v140, v118 row_newbcast:4 row_mask:0xf bank_mask:0xf
	v_mul_f32_dpp v131, -v140, v115 row_newbcast:1 row_mask:0xf bank_mask:0xf
	v_fmac_f32_dpp v132, -v140, v120 row_newbcast:6 row_mask:0xf bank_mask:0xf
	v_fmac_f32_dpp v133, -v140, v121 row_newbcast:7 row_mask:0xf bank_mask:0xf
	v_fmac_f32_dpp v130, -v140, v122 row_newbcast:8 row_mask:0xf bank_mask:0xf
	v_fmac_f32_dpp v131, -v140, v119 row_newbcast:5 row_mask:0xf bank_mask:0xf
	v_fmac_f32_dpp v132, -v140, v124 row_newbcast:10 row_mask:0xf bank_mask:0xf
	v_fmac_f32_dpp v133, -v140, v125 row_newbcast:11 row_mask:0xf bank_mask:0xf
	v_fmac_f32_dpp v130, -v140, v126 row_newbcast:12 row_mask:0xf bank_mask:0xf
	v_fmac_f32_dpp v131, -v140, v123 row_newbcast:9 row_mask:0xf bank_mask:0xf
	v_fmac_f32_dpp v132, -v140, v128 row_newbcast:14 row_mask:0xf bank_mask:0xf
	v_fmac_f32_dpp v133, -v140, v129 row_newbcast:15 row_mask:0xf bank_mask:0xf
	v_fmac_f32_dpp v131, -v140, v127 row_newbcast:13 row_mask:0xf bank_mask:0xf
	v_cndmask_b32_e64 v134, 0, 1.0, vcc
	v_add_f32_e32 v20, v130, v131
	v_add_f32_e32 v21, v132, v133
	v_add_f32_e32 v114, v20, v21
	ds_read_b32 v140, v138 offset:7648
	ds_read_b32 v141, v138 offset:7712
	s_waitcnt lgkmcnt(4)
	v_cmp_eq_u32_e32 vcc, 46, v139
	v_mul_f32_dpp v135, -v148, v115 row_newbcast:1 row_mask:0xf bank_mask:0xf
	v_mul_f32_dpp v136, -v148, v116 row_newbcast:2 row_mask:0xf bank_mask:0xf
	v_mul_f32_dpp v137, -v148, v117 row_newbcast:3 row_mask:0xf bank_mask:0xf
	v_fmac_f32_dpp v134, -v148, v114 row_newbcast:0 row_mask:0xf bank_mask:0xf
	v_fmac_f32_dpp v135, -v148, v119 row_newbcast:5 row_mask:0xf bank_mask:0xf
	v_fmac_f32_dpp v136, -v148, v120 row_newbcast:6 row_mask:0xf bank_mask:0xf
	v_fmac_f32_dpp v137, -v148, v121 row_newbcast:7 row_mask:0xf bank_mask:0xf
	v_fmac_f32_dpp v134, -v148, v118 row_newbcast:4 row_mask:0xf bank_mask:0xf
	v_fmac_f32_dpp v135, -v148, v123 row_newbcast:9 row_mask:0xf bank_mask:0xf
	v_fmac_f32_dpp v136, -v148, v124 row_newbcast:10 row_mask:0xf bank_mask:0xf
	v_fmac_f32_dpp v137, -v148, v125 row_newbcast:11 row_mask:0xf bank_mask:0xf
	v_fmac_f32_dpp v134, -v148, v122 row_newbcast:8 row_mask:0xf bank_mask:0xf
	v_fmac_f32_dpp v135, -v148, v127 row_newbcast:13 row_mask:0xf bank_mask:0xf
	v_fmac_f32_dpp v136, -v148, v128 row_newbcast:14 row_mask:0xf bank_mask:0xf
	v_fmac_f32_dpp v137, -v148, v129 row_newbcast:15 row_mask:0xf bank_mask:0xf
	v_fmac_f32_dpp v134, -v148, v126 row_newbcast:12 row_mask:0xf bank_mask:0xf
	v_cndmask_b32_e64 v130, 0, 1.0, vcc
	v_add_f32_e32 v20, v134, v135
	v_add_f32_e32 v21, v136, v137
	v_add_f32_e32 v113, v20, v21
	ds_read_b32 v148, v138 offset:7568
	ds_read_b32 v149, v138 offset:7632
	s_waitcnt lgkmcnt(4)
	v_cmp_eq_u32_e32 vcc, 45, v139
	v_fmac_f32_dpp v130, -v144, v114 row_newbcast:4 row_mask:0xf bank_mask:0xf
	v_mul_f32_dpp v131, -v144, v115 row_newbcast:5 row_mask:0xf bank_mask:0xf
	v_mul_f32_dpp v132, -v144, v116 row_newbcast:6 row_mask:0xf bank_mask:0xf
	v_mul_f32_dpp v133, -v144, v113 row_newbcast:3 row_mask:0xf bank_mask:0xf
	v_fmac_f32_dpp v130, -v144, v118 row_newbcast:8 row_mask:0xf bank_mask:0xf
	v_fmac_f32_dpp v131, -v144, v119 row_newbcast:9 row_mask:0xf bank_mask:0xf
	v_fmac_f32_dpp v132, -v144, v120 row_newbcast:10 row_mask:0xf bank_mask:0xf
	v_fmac_f32_dpp v133, -v144, v117 row_newbcast:7 row_mask:0xf bank_mask:0xf
	v_fmac_f32_dpp v130, -v144, v122 row_newbcast:12 row_mask:0xf bank_mask:0xf
	v_fmac_f32_dpp v131, -v144, v123 row_newbcast:13 row_mask:0xf bank_mask:0xf
	v_fmac_f32_dpp v132, -v144, v124 row_newbcast:14 row_mask:0xf bank_mask:0xf
	v_fmac_f32_dpp v133, -v144, v121 row_newbcast:11 row_mask:0xf bank_mask:0xf
	v_fmac_f32_dpp v130, -v145, v126 row_newbcast:0 row_mask:0xf bank_mask:0xf
	v_fmac_f32_dpp v131, -v145, v127 row_newbcast:1 row_mask:0xf bank_mask:0xf
	v_fmac_f32_dpp v132, -v145, v128 row_newbcast:2 row_mask:0xf bank_mask:0xf
	v_fmac_f32_dpp v133, -v144, v125 row_newbcast:15 row_mask:0xf bank_mask:0xf
	s_nop 1
	v_fmac_f32_dpp v133, -v145, v129 row_newbcast:3 row_mask:0xf bank_mask:0xf
	v_cndmask_b32_e64 v134, 0, 1.0, vcc
	v_add_f32_e32 v20, v130, v131
	v_add_f32_e32 v21, v132, v133
	v_add_f32_e32 v112, v20, v21
	ds_read_b32 v144, v138 offset:7488
	ds_read_b32 v145, v138 offset:7552
	s_waitcnt lgkmcnt(4)
	v_cmp_eq_u32_e32 vcc, 44, v139
	v_mul_f32_dpp v137, -v140, v113 row_newbcast:3 row_mask:0xf bank_mask:0xf
	v_fmac_f32_dpp v134, -v140, v114 row_newbcast:4 row_mask:0xf bank_mask:0xf
	v_mul_f32_dpp v135, -v140, v115 row_newbcast:5 row_mask:0xf bank_mask:0xf
	v_mul_f32_dpp v136, -v140, v112 row_newbcast:2 row_mask:0xf bank_mask:0xf
	v_fmac_f32_dpp v137, -v140, v117 row_newbcast:7 row_mask:0xf bank_mask:0xf
	v_fmac_f32_dpp v134, -v140, v118 row_newbcast:8 row_mask:0xf bank_mask:0xf
	v_fmac_f32_dpp v135, -v140, v119 row_newbcast:9 row_mask:0xf bank_mask:0xf
	v_fmac_f32_dpp v136, -v140, v116 row_newbcast:6 row_mask:0xf bank_mask:0xf
	v_fmac_f32_dpp v137, -v140, v121 row_newbcast:11 row_mask:0xf bank_mask:0xf
	v_fmac_f32_dpp v134, -v140, v122 row_newbcast:12 row_mask:0xf bank_mask:0xf
	v_fmac_f32_dpp v135, -v140, v123 row_newbcast:13 row_mask:0xf bank_mask:0xf
	v_fmac_f32_dpp v136, -v140, v120 row_newbcast:10 row_mask:0xf bank_mask:0xf
	v_fmac_f32_dpp v137, -v140, v125 row_newbcast:15 row_mask:0xf bank_mask:0xf
	v_fmac_f32_dpp v134, -v141, v126 row_newbcast:0 row_mask:0xf bank_mask:0xf
	v_fmac_f32_dpp v135, -v141, v127 row_newbcast:1 row_mask:0xf bank_mask:0xf
	v_fmac_f32_dpp v136, -v140, v124 row_newbcast:14 row_mask:0xf bank_mask:0xf
	v_fmac_f32_dpp v137, -v141, v129 row_newbcast:3 row_mask:0xf bank_mask:0xf
	s_nop 0
	v_fmac_f32_dpp v136, -v141, v128 row_newbcast:2 row_mask:0xf bank_mask:0xf
	v_cndmask_b32_e64 v130, 0, 1.0, vcc
	v_add_f32_e32 v20, v134, v135
	v_add_f32_e32 v21, v136, v137
	v_add_f32_e32 v111, v20, v21
	ds_read_b32 v140, v138 offset:7392
	ds_read_b32 v141, v138 offset:7456
	s_waitcnt lgkmcnt(4)
	v_cmp_eq_u32_e32 vcc, 43, v139
	v_mul_f32_dpp v132, -v148, v112 row_newbcast:2 row_mask:0xf bank_mask:0xf
	v_mul_f32_dpp v133, -v148, v113 row_newbcast:3 row_mask:0xf bank_mask:0xf
	v_fmac_f32_dpp v130, -v148, v114 row_newbcast:4 row_mask:0xf bank_mask:0xf
	v_mul_f32_dpp v131, -v148, v111 row_newbcast:1 row_mask:0xf bank_mask:0xf
	v_fmac_f32_dpp v132, -v148, v116 row_newbcast:6 row_mask:0xf bank_mask:0xf
	v_fmac_f32_dpp v133, -v148, v117 row_newbcast:7 row_mask:0xf bank_mask:0xf
	v_fmac_f32_dpp v130, -v148, v118 row_newbcast:8 row_mask:0xf bank_mask:0xf
	v_fmac_f32_dpp v131, -v148, v115 row_newbcast:5 row_mask:0xf bank_mask:0xf
	v_fmac_f32_dpp v132, -v148, v120 row_newbcast:10 row_mask:0xf bank_mask:0xf
	v_fmac_f32_dpp v133, -v148, v121 row_newbcast:11 row_mask:0xf bank_mask:0xf
	v_fmac_f32_dpp v130, -v148, v122 row_newbcast:12 row_mask:0xf bank_mask:0xf
	v_fmac_f32_dpp v131, -v148, v119 row_newbcast:9 row_mask:0xf bank_mask:0xf
	v_fmac_f32_dpp v132, -v148, v124 row_newbcast:14 row_mask:0xf bank_mask:0xf
	v_fmac_f32_dpp v133, -v148, v125 row_newbcast:15 row_mask:0xf bank_mask:0xf
	v_fmac_f32_dpp v130, -v149, v126 row_newbcast:0 row_mask:0xf bank_mask:0xf
	v_fmac_f32_dpp v131, -v148, v123 row_newbcast:13 row_mask:0xf bank_mask:0xf
	v_fmac_f32_dpp v132, -v149, v128 row_newbcast:2 row_mask:0xf bank_mask:0xf
	v_fmac_f32_dpp v133, -v149, v129 row_newbcast:3 row_mask:0xf bank_mask:0xf
	v_fmac_f32_dpp v131, -v149, v127 row_newbcast:1 row_mask:0xf bank_mask:0xf
	v_cndmask_b32_e64 v134, 0, 1.0, vcc
	v_add_f32_e32 v20, v130, v131
	v_add_f32_e32 v21, v132, v133
	v_add_f32_e32 v110, v20, v21
	ds_read_b32 v148, v138 offset:7296
	ds_read_b32 v149, v138 offset:7360
	s_waitcnt lgkmcnt(4)
	v_cmp_eq_u32_e32 vcc, 42, v139
	v_mul_f32_dpp v135, -v144, v111 row_newbcast:1 row_mask:0xf bank_mask:0xf
	v_mul_f32_dpp v136, -v144, v112 row_newbcast:2 row_mask:0xf bank_mask:0xf
	v_mul_f32_dpp v137, -v144, v113 row_newbcast:3 row_mask:0xf bank_mask:0xf
	v_fmac_f32_dpp v134, -v144, v110 row_newbcast:0 row_mask:0xf bank_mask:0xf
	v_fmac_f32_dpp v135, -v144, v115 row_newbcast:5 row_mask:0xf bank_mask:0xf
	v_fmac_f32_dpp v136, -v144, v116 row_newbcast:6 row_mask:0xf bank_mask:0xf
	v_fmac_f32_dpp v137, -v144, v117 row_newbcast:7 row_mask:0xf bank_mask:0xf
	v_fmac_f32_dpp v134, -v144, v114 row_newbcast:4 row_mask:0xf bank_mask:0xf
	v_fmac_f32_dpp v135, -v144, v119 row_newbcast:9 row_mask:0xf bank_mask:0xf
	v_fmac_f32_dpp v136, -v144, v120 row_newbcast:10 row_mask:0xf bank_mask:0xf
	v_fmac_f32_dpp v137, -v144, v121 row_newbcast:11 row_mask:0xf bank_mask:0xf
	v_fmac_f32_dpp v134, -v144, v118 row_newbcast:8 row_mask:0xf bank_mask:0xf
	v_fmac_f32_dpp v135, -v144, v123 row_newbcast:13 row_mask:0xf bank_mask:0xf
	v_fmac_f32_dpp v136, -v144, v124 row_newbcast:14 row_mask:0xf bank_mask:0xf
	v_fmac_f32_dpp v137, -v144, v125 row_newbcast:15 row_mask:0xf bank_mask:0xf
	v_fmac_f32_dpp v134, -v144, v122 row_newbcast:12 row_mask:0xf bank_mask:0xf
	v_fmac_f32_dpp v135, -v145, v127 row_newbcast:1 row_mask:0xf bank_mask:0xf
	v_fmac_f32_dpp v136, -v145, v128 row_newbcast:2 row_mask:0xf bank_mask:0xf
	v_fmac_f32_dpp v137, -v145, v129 row_newbcast:3 row_mask:0xf bank_mask:0xf
	v_fmac_f32_dpp v134, -v145, v126 row_newbcast:0 row_mask:0xf bank_mask:0xf
	v_cndmask_b32_e64 v130, 0, 1.0, vcc
	v_add_f32_e32 v20, v134, v135
	v_add_f32_e32 v21, v136, v137
	v_add_f32_e32 v109, v20, v21
	ds_read_b32 v144, v138 offset:7200
	ds_read_b32 v145, v138 offset:7264
	s_waitcnt lgkmcnt(4)
	v_cmp_eq_u32_e32 vcc, 41, v139
	v_fmac_f32_dpp v130, -v140, v110 row_newbcast:4 row_mask:0xf bank_mask:0xf
	v_mul_f32_dpp v131, -v140, v111 row_newbcast:5 row_mask:0xf bank_mask:0xf
	v_mul_f32_dpp v132, -v140, v112 row_newbcast:6 row_mask:0xf bank_mask:0xf
	v_mul_f32_dpp v133, -v140, v109 row_newbcast:3 row_mask:0xf bank_mask:0xf
	v_fmac_f32_dpp v130, -v140, v114 row_newbcast:8 row_mask:0xf bank_mask:0xf
	v_fmac_f32_dpp v131, -v140, v115 row_newbcast:9 row_mask:0xf bank_mask:0xf
	v_fmac_f32_dpp v132, -v140, v116 row_newbcast:10 row_mask:0xf bank_mask:0xf
	v_fmac_f32_dpp v133, -v140, v113 row_newbcast:7 row_mask:0xf bank_mask:0xf
	v_fmac_f32_dpp v130, -v140, v118 row_newbcast:12 row_mask:0xf bank_mask:0xf
	v_fmac_f32_dpp v131, -v140, v119 row_newbcast:13 row_mask:0xf bank_mask:0xf
	v_fmac_f32_dpp v132, -v140, v120 row_newbcast:14 row_mask:0xf bank_mask:0xf
	v_fmac_f32_dpp v133, -v140, v117 row_newbcast:11 row_mask:0xf bank_mask:0xf
	v_fmac_f32_dpp v130, -v141, v122 row_newbcast:0 row_mask:0xf bank_mask:0xf
	v_fmac_f32_dpp v131, -v141, v123 row_newbcast:1 row_mask:0xf bank_mask:0xf
	v_fmac_f32_dpp v132, -v141, v124 row_newbcast:2 row_mask:0xf bank_mask:0xf
	v_fmac_f32_dpp v133, -v140, v121 row_newbcast:15 row_mask:0xf bank_mask:0xf
	v_fmac_f32_dpp v130, -v141, v126 row_newbcast:4 row_mask:0xf bank_mask:0xf
	v_fmac_f32_dpp v131, -v141, v127 row_newbcast:5 row_mask:0xf bank_mask:0xf
	v_fmac_f32_dpp v132, -v141, v128 row_newbcast:6 row_mask:0xf bank_mask:0xf
	v_fmac_f32_dpp v133, -v141, v125 row_newbcast:3 row_mask:0xf bank_mask:0xf
	s_nop 1
	v_fmac_f32_dpp v133, -v141, v129 row_newbcast:7 row_mask:0xf bank_mask:0xf
	v_cndmask_b32_e64 v134, 0, 1.0, vcc
	v_add_f32_e32 v20, v130, v131
	v_add_f32_e32 v21, v132, v133
	v_add_f32_e32 v108, v20, v21
	ds_read_b32 v140, v138 offset:7104
	ds_read_b32 v141, v138 offset:7168
	s_waitcnt lgkmcnt(4)
	v_cmp_eq_u32_e32 vcc, 40, v139
	v_mul_f32_dpp v137, -v148, v109 row_newbcast:3 row_mask:0xf bank_mask:0xf
	v_fmac_f32_dpp v134, -v148, v110 row_newbcast:4 row_mask:0xf bank_mask:0xf
	v_mul_f32_dpp v135, -v148, v111 row_newbcast:5 row_mask:0xf bank_mask:0xf
	v_mul_f32_dpp v136, -v148, v108 row_newbcast:2 row_mask:0xf bank_mask:0xf
	v_fmac_f32_dpp v137, -v148, v113 row_newbcast:7 row_mask:0xf bank_mask:0xf
	v_fmac_f32_dpp v134, -v148, v114 row_newbcast:8 row_mask:0xf bank_mask:0xf
	v_fmac_f32_dpp v135, -v148, v115 row_newbcast:9 row_mask:0xf bank_mask:0xf
	v_fmac_f32_dpp v136, -v148, v112 row_newbcast:6 row_mask:0xf bank_mask:0xf
	v_fmac_f32_dpp v137, -v148, v117 row_newbcast:11 row_mask:0xf bank_mask:0xf
	v_fmac_f32_dpp v134, -v148, v118 row_newbcast:12 row_mask:0xf bank_mask:0xf
	v_fmac_f32_dpp v135, -v148, v119 row_newbcast:13 row_mask:0xf bank_mask:0xf
	v_fmac_f32_dpp v136, -v148, v116 row_newbcast:10 row_mask:0xf bank_mask:0xf
	v_fmac_f32_dpp v137, -v148, v121 row_newbcast:15 row_mask:0xf bank_mask:0xf
	v_fmac_f32_dpp v134, -v149, v122 row_newbcast:0 row_mask:0xf bank_mask:0xf
	v_fmac_f32_dpp v135, -v149, v123 row_newbcast:1 row_mask:0xf bank_mask:0xf
	v_fmac_f32_dpp v136, -v148, v120 row_newbcast:14 row_mask:0xf bank_mask:0xf
	v_fmac_f32_dpp v137, -v149, v125 row_newbcast:3 row_mask:0xf bank_mask:0xf
	v_fmac_f32_dpp v134, -v149, v126 row_newbcast:4 row_mask:0xf bank_mask:0xf
	v_fmac_f32_dpp v135, -v149, v127 row_newbcast:5 row_mask:0xf bank_mask:0xf
	v_fmac_f32_dpp v136, -v149, v124 row_newbcast:2 row_mask:0xf bank_mask:0xf
	v_fmac_f32_dpp v137, -v149, v129 row_newbcast:7 row_mask:0xf bank_mask:0xf
	s_nop 0
	v_fmac_f32_dpp v136, -v149, v128 row_newbcast:6 row_mask:0xf bank_mask:0xf
	v_cndmask_b32_e64 v130, 0, 1.0, vcc
	v_add_f32_e32 v20, v134, v135
	v_add_f32_e32 v21, v136, v137
	v_add_f32_e32 v107, v20, v21
	ds_read_b32 v148, v138 offset:6992
	ds_read_b32 v149, v138 offset:7056
	s_waitcnt lgkmcnt(4)
	v_cmp_eq_u32_e32 vcc, 39, v139
	v_mul_f32_dpp v132, -v144, v108 row_newbcast:2 row_mask:0xf bank_mask:0xf
	v_mul_f32_dpp v133, -v144, v109 row_newbcast:3 row_mask:0xf bank_mask:0xf
	v_fmac_f32_dpp v130, -v144, v110 row_newbcast:4 row_mask:0xf bank_mask:0xf
	v_mul_f32_dpp v131, -v144, v107 row_newbcast:1 row_mask:0xf bank_mask:0xf
	v_fmac_f32_dpp v132, -v144, v112 row_newbcast:6 row_mask:0xf bank_mask:0xf
	v_fmac_f32_dpp v133, -v144, v113 row_newbcast:7 row_mask:0xf bank_mask:0xf
	v_fmac_f32_dpp v130, -v144, v114 row_newbcast:8 row_mask:0xf bank_mask:0xf
	v_fmac_f32_dpp v131, -v144, v111 row_newbcast:5 row_mask:0xf bank_mask:0xf
	v_fmac_f32_dpp v132, -v144, v116 row_newbcast:10 row_mask:0xf bank_mask:0xf
	v_fmac_f32_dpp v133, -v144, v117 row_newbcast:11 row_mask:0xf bank_mask:0xf
	v_fmac_f32_dpp v130, -v144, v118 row_newbcast:12 row_mask:0xf bank_mask:0xf
	v_fmac_f32_dpp v131, -v144, v115 row_newbcast:9 row_mask:0xf bank_mask:0xf
	v_fmac_f32_dpp v132, -v144, v120 row_newbcast:14 row_mask:0xf bank_mask:0xf
	v_fmac_f32_dpp v133, -v144, v121 row_newbcast:15 row_mask:0xf bank_mask:0xf
	v_fmac_f32_dpp v130, -v145, v122 row_newbcast:0 row_mask:0xf bank_mask:0xf
	v_fmac_f32_dpp v131, -v144, v119 row_newbcast:13 row_mask:0xf bank_mask:0xf
	v_fmac_f32_dpp v132, -v145, v124 row_newbcast:2 row_mask:0xf bank_mask:0xf
	v_fmac_f32_dpp v133, -v145, v125 row_newbcast:3 row_mask:0xf bank_mask:0xf
	v_fmac_f32_dpp v130, -v145, v126 row_newbcast:4 row_mask:0xf bank_mask:0xf
	v_fmac_f32_dpp v131, -v145, v123 row_newbcast:1 row_mask:0xf bank_mask:0xf
	v_fmac_f32_dpp v132, -v145, v128 row_newbcast:6 row_mask:0xf bank_mask:0xf
	v_fmac_f32_dpp v133, -v145, v129 row_newbcast:7 row_mask:0xf bank_mask:0xf
	v_fmac_f32_dpp v131, -v145, v127 row_newbcast:5 row_mask:0xf bank_mask:0xf
	v_cndmask_b32_e64 v134, 0, 1.0, vcc
	v_add_f32_e32 v20, v130, v131
	v_add_f32_e32 v21, v132, v133
	v_add_f32_e32 v106, v20, v21
	ds_read_b32 v144, v138 offset:6880
	ds_read_b32 v145, v138 offset:6944
	s_waitcnt lgkmcnt(4)
	v_cmp_eq_u32_e32 vcc, 38, v139
	v_mul_f32_dpp v135, -v140, v107 row_newbcast:1 row_mask:0xf bank_mask:0xf
	v_mul_f32_dpp v136, -v140, v108 row_newbcast:2 row_mask:0xf bank_mask:0xf
	v_mul_f32_dpp v137, -v140, v109 row_newbcast:3 row_mask:0xf bank_mask:0xf
	v_fmac_f32_dpp v134, -v140, v106 row_newbcast:0 row_mask:0xf bank_mask:0xf
	v_fmac_f32_dpp v135, -v140, v111 row_newbcast:5 row_mask:0xf bank_mask:0xf
	v_fmac_f32_dpp v136, -v140, v112 row_newbcast:6 row_mask:0xf bank_mask:0xf
	v_fmac_f32_dpp v137, -v140, v113 row_newbcast:7 row_mask:0xf bank_mask:0xf
	v_fmac_f32_dpp v134, -v140, v110 row_newbcast:4 row_mask:0xf bank_mask:0xf
	v_fmac_f32_dpp v135, -v140, v115 row_newbcast:9 row_mask:0xf bank_mask:0xf
	v_fmac_f32_dpp v136, -v140, v116 row_newbcast:10 row_mask:0xf bank_mask:0xf
	v_fmac_f32_dpp v137, -v140, v117 row_newbcast:11 row_mask:0xf bank_mask:0xf
	v_fmac_f32_dpp v134, -v140, v114 row_newbcast:8 row_mask:0xf bank_mask:0xf
	v_fmac_f32_dpp v135, -v140, v119 row_newbcast:13 row_mask:0xf bank_mask:0xf
	v_fmac_f32_dpp v136, -v140, v120 row_newbcast:14 row_mask:0xf bank_mask:0xf
	v_fmac_f32_dpp v137, -v140, v121 row_newbcast:15 row_mask:0xf bank_mask:0xf
	v_fmac_f32_dpp v134, -v140, v118 row_newbcast:12 row_mask:0xf bank_mask:0xf
	v_fmac_f32_dpp v135, -v141, v123 row_newbcast:1 row_mask:0xf bank_mask:0xf
	v_fmac_f32_dpp v136, -v141, v124 row_newbcast:2 row_mask:0xf bank_mask:0xf
	v_fmac_f32_dpp v137, -v141, v125 row_newbcast:3 row_mask:0xf bank_mask:0xf
	v_fmac_f32_dpp v134, -v141, v122 row_newbcast:0 row_mask:0xf bank_mask:0xf
	v_fmac_f32_dpp v135, -v141, v127 row_newbcast:5 row_mask:0xf bank_mask:0xf
	v_fmac_f32_dpp v136, -v141, v128 row_newbcast:6 row_mask:0xf bank_mask:0xf
	v_fmac_f32_dpp v137, -v141, v129 row_newbcast:7 row_mask:0xf bank_mask:0xf
	v_fmac_f32_dpp v134, -v141, v126 row_newbcast:4 row_mask:0xf bank_mask:0xf
	v_cndmask_b32_e64 v130, 0, 1.0, vcc
	v_add_f32_e32 v20, v134, v135
	v_add_f32_e32 v21, v136, v137
	v_add_f32_e32 v105, v20, v21
	ds_read_b32 v140, v138 offset:6768
	ds_read_b32 v141, v138 offset:6832
	s_waitcnt lgkmcnt(4)
	v_cmp_eq_u32_e32 vcc, 37, v139
	v_fmac_f32_dpp v130, -v148, v106 row_newbcast:4 row_mask:0xf bank_mask:0xf
	v_mul_f32_dpp v131, -v148, v107 row_newbcast:5 row_mask:0xf bank_mask:0xf
	v_mul_f32_dpp v132, -v148, v108 row_newbcast:6 row_mask:0xf bank_mask:0xf
	v_mul_f32_dpp v133, -v148, v105 row_newbcast:3 row_mask:0xf bank_mask:0xf
	v_fmac_f32_dpp v130, -v148, v110 row_newbcast:8 row_mask:0xf bank_mask:0xf
	v_fmac_f32_dpp v131, -v148, v111 row_newbcast:9 row_mask:0xf bank_mask:0xf
	v_fmac_f32_dpp v132, -v148, v112 row_newbcast:10 row_mask:0xf bank_mask:0xf
	v_fmac_f32_dpp v133, -v148, v109 row_newbcast:7 row_mask:0xf bank_mask:0xf
	v_fmac_f32_dpp v130, -v148, v114 row_newbcast:12 row_mask:0xf bank_mask:0xf
	v_fmac_f32_dpp v131, -v148, v115 row_newbcast:13 row_mask:0xf bank_mask:0xf
	v_fmac_f32_dpp v132, -v148, v116 row_newbcast:14 row_mask:0xf bank_mask:0xf
	v_fmac_f32_dpp v133, -v148, v113 row_newbcast:11 row_mask:0xf bank_mask:0xf
	v_fmac_f32_dpp v130, -v149, v118 row_newbcast:0 row_mask:0xf bank_mask:0xf
	v_fmac_f32_dpp v131, -v149, v119 row_newbcast:1 row_mask:0xf bank_mask:0xf
	v_fmac_f32_dpp v132, -v149, v120 row_newbcast:2 row_mask:0xf bank_mask:0xf
	v_fmac_f32_dpp v133, -v148, v117 row_newbcast:15 row_mask:0xf bank_mask:0xf
	v_fmac_f32_dpp v130, -v149, v122 row_newbcast:4 row_mask:0xf bank_mask:0xf
	v_fmac_f32_dpp v131, -v149, v123 row_newbcast:5 row_mask:0xf bank_mask:0xf
	v_fmac_f32_dpp v132, -v149, v124 row_newbcast:6 row_mask:0xf bank_mask:0xf
	v_fmac_f32_dpp v133, -v149, v121 row_newbcast:3 row_mask:0xf bank_mask:0xf
	v_fmac_f32_dpp v130, -v149, v126 row_newbcast:8 row_mask:0xf bank_mask:0xf
	v_fmac_f32_dpp v131, -v149, v127 row_newbcast:9 row_mask:0xf bank_mask:0xf
	v_fmac_f32_dpp v132, -v149, v128 row_newbcast:10 row_mask:0xf bank_mask:0xf
	v_fmac_f32_dpp v133, -v149, v125 row_newbcast:7 row_mask:0xf bank_mask:0xf
	s_nop 1
	v_fmac_f32_dpp v133, -v149, v129 row_newbcast:11 row_mask:0xf bank_mask:0xf
	v_cndmask_b32_e64 v134, 0, 1.0, vcc
	v_add_f32_e32 v20, v130, v131
	v_add_f32_e32 v21, v132, v133
	v_add_f32_e32 v104, v20, v21
	ds_read_b32 v148, v138 offset:6656
	ds_read_b32 v149, v138 offset:6720
	s_waitcnt lgkmcnt(4)
	v_cmp_eq_u32_e32 vcc, 36, v139
	v_mul_f32_dpp v137, -v144, v105 row_newbcast:3 row_mask:0xf bank_mask:0xf
	v_fmac_f32_dpp v134, -v144, v106 row_newbcast:4 row_mask:0xf bank_mask:0xf
	v_mul_f32_dpp v135, -v144, v107 row_newbcast:5 row_mask:0xf bank_mask:0xf
	v_mul_f32_dpp v136, -v144, v104 row_newbcast:2 row_mask:0xf bank_mask:0xf
	v_fmac_f32_dpp v137, -v144, v109 row_newbcast:7 row_mask:0xf bank_mask:0xf
	v_fmac_f32_dpp v134, -v144, v110 row_newbcast:8 row_mask:0xf bank_mask:0xf
	v_fmac_f32_dpp v135, -v144, v111 row_newbcast:9 row_mask:0xf bank_mask:0xf
	v_fmac_f32_dpp v136, -v144, v108 row_newbcast:6 row_mask:0xf bank_mask:0xf
	v_fmac_f32_dpp v137, -v144, v113 row_newbcast:11 row_mask:0xf bank_mask:0xf
	v_fmac_f32_dpp v134, -v144, v114 row_newbcast:12 row_mask:0xf bank_mask:0xf
	v_fmac_f32_dpp v135, -v144, v115 row_newbcast:13 row_mask:0xf bank_mask:0xf
	v_fmac_f32_dpp v136, -v144, v112 row_newbcast:10 row_mask:0xf bank_mask:0xf
	v_fmac_f32_dpp v137, -v144, v117 row_newbcast:15 row_mask:0xf bank_mask:0xf
	v_fmac_f32_dpp v134, -v145, v118 row_newbcast:0 row_mask:0xf bank_mask:0xf
	v_fmac_f32_dpp v135, -v145, v119 row_newbcast:1 row_mask:0xf bank_mask:0xf
	v_fmac_f32_dpp v136, -v144, v116 row_newbcast:14 row_mask:0xf bank_mask:0xf
	v_fmac_f32_dpp v137, -v145, v121 row_newbcast:3 row_mask:0xf bank_mask:0xf
	v_fmac_f32_dpp v134, -v145, v122 row_newbcast:4 row_mask:0xf bank_mask:0xf
	v_fmac_f32_dpp v135, -v145, v123 row_newbcast:5 row_mask:0xf bank_mask:0xf
	v_fmac_f32_dpp v136, -v145, v120 row_newbcast:2 row_mask:0xf bank_mask:0xf
	v_fmac_f32_dpp v137, -v145, v125 row_newbcast:7 row_mask:0xf bank_mask:0xf
	v_fmac_f32_dpp v134, -v145, v126 row_newbcast:8 row_mask:0xf bank_mask:0xf
	v_fmac_f32_dpp v135, -v145, v127 row_newbcast:9 row_mask:0xf bank_mask:0xf
	v_fmac_f32_dpp v136, -v145, v124 row_newbcast:6 row_mask:0xf bank_mask:0xf
	v_fmac_f32_dpp v137, -v145, v129 row_newbcast:11 row_mask:0xf bank_mask:0xf
	s_nop 0
	v_fmac_f32_dpp v136, -v145, v128 row_newbcast:10 row_mask:0xf bank_mask:0xf
	v_cndmask_b32_e64 v130, 0, 1.0, vcc
	v_add_f32_e32 v20, v134, v135
	v_add_f32_e32 v21, v136, v137
	v_add_f32_e32 v103, v20, v21
	ds_read_b32 v144, v138 offset:6528
	ds_read_b32 v145, v138 offset:6592
	s_waitcnt lgkmcnt(4)
	v_cmp_eq_u32_e32 vcc, 35, v139
	v_mul_f32_dpp v132, -v140, v104 row_newbcast:2 row_mask:0xf bank_mask:0xf
	v_mul_f32_dpp v133, -v140, v105 row_newbcast:3 row_mask:0xf bank_mask:0xf
	v_fmac_f32_dpp v130, -v140, v106 row_newbcast:4 row_mask:0xf bank_mask:0xf
	v_mul_f32_dpp v131, -v140, v103 row_newbcast:1 row_mask:0xf bank_mask:0xf
	v_fmac_f32_dpp v132, -v140, v108 row_newbcast:6 row_mask:0xf bank_mask:0xf
	v_fmac_f32_dpp v133, -v140, v109 row_newbcast:7 row_mask:0xf bank_mask:0xf
	v_fmac_f32_dpp v130, -v140, v110 row_newbcast:8 row_mask:0xf bank_mask:0xf
	v_fmac_f32_dpp v131, -v140, v107 row_newbcast:5 row_mask:0xf bank_mask:0xf
	v_fmac_f32_dpp v132, -v140, v112 row_newbcast:10 row_mask:0xf bank_mask:0xf
	v_fmac_f32_dpp v133, -v140, v113 row_newbcast:11 row_mask:0xf bank_mask:0xf
	v_fmac_f32_dpp v130, -v140, v114 row_newbcast:12 row_mask:0xf bank_mask:0xf
	v_fmac_f32_dpp v131, -v140, v111 row_newbcast:9 row_mask:0xf bank_mask:0xf
	v_fmac_f32_dpp v132, -v140, v116 row_newbcast:14 row_mask:0xf bank_mask:0xf
	v_fmac_f32_dpp v133, -v140, v117 row_newbcast:15 row_mask:0xf bank_mask:0xf
	v_fmac_f32_dpp v130, -v141, v118 row_newbcast:0 row_mask:0xf bank_mask:0xf
	v_fmac_f32_dpp v131, -v140, v115 row_newbcast:13 row_mask:0xf bank_mask:0xf
	v_fmac_f32_dpp v132, -v141, v120 row_newbcast:2 row_mask:0xf bank_mask:0xf
	v_fmac_f32_dpp v133, -v141, v121 row_newbcast:3 row_mask:0xf bank_mask:0xf
	v_fmac_f32_dpp v130, -v141, v122 row_newbcast:4 row_mask:0xf bank_mask:0xf
	v_fmac_f32_dpp v131, -v141, v119 row_newbcast:1 row_mask:0xf bank_mask:0xf
	v_fmac_f32_dpp v132, -v141, v124 row_newbcast:6 row_mask:0xf bank_mask:0xf
	v_fmac_f32_dpp v133, -v141, v125 row_newbcast:7 row_mask:0xf bank_mask:0xf
	v_fmac_f32_dpp v130, -v141, v126 row_newbcast:8 row_mask:0xf bank_mask:0xf
	v_fmac_f32_dpp v131, -v141, v123 row_newbcast:5 row_mask:0xf bank_mask:0xf
	v_fmac_f32_dpp v132, -v141, v128 row_newbcast:10 row_mask:0xf bank_mask:0xf
	v_fmac_f32_dpp v133, -v141, v129 row_newbcast:11 row_mask:0xf bank_mask:0xf
	v_fmac_f32_dpp v131, -v141, v127 row_newbcast:9 row_mask:0xf bank_mask:0xf
	v_cndmask_b32_e64 v134, 0, 1.0, vcc
	v_add_f32_e32 v20, v130, v131
	v_add_f32_e32 v21, v132, v133
	v_add_f32_e32 v102, v20, v21
	ds_read_b32 v140, v138 offset:6400
	ds_read_b32 v141, v138 offset:6464
	s_waitcnt lgkmcnt(4)
	v_cmp_eq_u32_e32 vcc, 34, v139
	v_mul_f32_dpp v135, -v148, v103 row_newbcast:1 row_mask:0xf bank_mask:0xf
	v_mul_f32_dpp v136, -v148, v104 row_newbcast:2 row_mask:0xf bank_mask:0xf
	v_mul_f32_dpp v137, -v148, v105 row_newbcast:3 row_mask:0xf bank_mask:0xf
	v_fmac_f32_dpp v134, -v148, v102 row_newbcast:0 row_mask:0xf bank_mask:0xf
	v_fmac_f32_dpp v135, -v148, v107 row_newbcast:5 row_mask:0xf bank_mask:0xf
	v_fmac_f32_dpp v136, -v148, v108 row_newbcast:6 row_mask:0xf bank_mask:0xf
	v_fmac_f32_dpp v137, -v148, v109 row_newbcast:7 row_mask:0xf bank_mask:0xf
	v_fmac_f32_dpp v134, -v148, v106 row_newbcast:4 row_mask:0xf bank_mask:0xf
	v_fmac_f32_dpp v135, -v148, v111 row_newbcast:9 row_mask:0xf bank_mask:0xf
	v_fmac_f32_dpp v136, -v148, v112 row_newbcast:10 row_mask:0xf bank_mask:0xf
	v_fmac_f32_dpp v137, -v148, v113 row_newbcast:11 row_mask:0xf bank_mask:0xf
	v_fmac_f32_dpp v134, -v148, v110 row_newbcast:8 row_mask:0xf bank_mask:0xf
	v_fmac_f32_dpp v135, -v148, v115 row_newbcast:13 row_mask:0xf bank_mask:0xf
	v_fmac_f32_dpp v136, -v148, v116 row_newbcast:14 row_mask:0xf bank_mask:0xf
	v_fmac_f32_dpp v137, -v148, v117 row_newbcast:15 row_mask:0xf bank_mask:0xf
	v_fmac_f32_dpp v134, -v148, v114 row_newbcast:12 row_mask:0xf bank_mask:0xf
	v_fmac_f32_dpp v135, -v149, v119 row_newbcast:1 row_mask:0xf bank_mask:0xf
	v_fmac_f32_dpp v136, -v149, v120 row_newbcast:2 row_mask:0xf bank_mask:0xf
	v_fmac_f32_dpp v137, -v149, v121 row_newbcast:3 row_mask:0xf bank_mask:0xf
	v_fmac_f32_dpp v134, -v149, v118 row_newbcast:0 row_mask:0xf bank_mask:0xf
	v_fmac_f32_dpp v135, -v149, v123 row_newbcast:5 row_mask:0xf bank_mask:0xf
	v_fmac_f32_dpp v136, -v149, v124 row_newbcast:6 row_mask:0xf bank_mask:0xf
	v_fmac_f32_dpp v137, -v149, v125 row_newbcast:7 row_mask:0xf bank_mask:0xf
	v_fmac_f32_dpp v134, -v149, v122 row_newbcast:4 row_mask:0xf bank_mask:0xf
	v_fmac_f32_dpp v135, -v149, v127 row_newbcast:9 row_mask:0xf bank_mask:0xf
	v_fmac_f32_dpp v136, -v149, v128 row_newbcast:10 row_mask:0xf bank_mask:0xf
	v_fmac_f32_dpp v137, -v149, v129 row_newbcast:11 row_mask:0xf bank_mask:0xf
	v_fmac_f32_dpp v134, -v149, v126 row_newbcast:8 row_mask:0xf bank_mask:0xf
	v_cndmask_b32_e64 v130, 0, 1.0, vcc
	v_add_f32_e32 v20, v134, v135
	v_add_f32_e32 v21, v136, v137
	v_add_f32_e32 v101, v20, v21
	ds_read_b32 v148, v138 offset:6272
	ds_read_b32 v149, v138 offset:6336
	s_waitcnt lgkmcnt(4)
	v_cmp_eq_u32_e32 vcc, 33, v139
	v_fmac_f32_dpp v130, -v144, v102 row_newbcast:4 row_mask:0xf bank_mask:0xf
	v_mul_f32_dpp v131, -v144, v103 row_newbcast:5 row_mask:0xf bank_mask:0xf
	v_mul_f32_dpp v132, -v144, v104 row_newbcast:6 row_mask:0xf bank_mask:0xf
	v_mul_f32_dpp v133, -v144, v101 row_newbcast:3 row_mask:0xf bank_mask:0xf
	v_fmac_f32_dpp v130, -v144, v106 row_newbcast:8 row_mask:0xf bank_mask:0xf
	v_fmac_f32_dpp v131, -v144, v107 row_newbcast:9 row_mask:0xf bank_mask:0xf
	v_fmac_f32_dpp v132, -v144, v108 row_newbcast:10 row_mask:0xf bank_mask:0xf
	v_fmac_f32_dpp v133, -v144, v105 row_newbcast:7 row_mask:0xf bank_mask:0xf
	v_fmac_f32_dpp v130, -v144, v110 row_newbcast:12 row_mask:0xf bank_mask:0xf
	v_fmac_f32_dpp v131, -v144, v111 row_newbcast:13 row_mask:0xf bank_mask:0xf
	v_fmac_f32_dpp v132, -v144, v112 row_newbcast:14 row_mask:0xf bank_mask:0xf
	v_fmac_f32_dpp v133, -v144, v109 row_newbcast:11 row_mask:0xf bank_mask:0xf
	v_fmac_f32_dpp v130, -v145, v114 row_newbcast:0 row_mask:0xf bank_mask:0xf
	v_fmac_f32_dpp v131, -v145, v115 row_newbcast:1 row_mask:0xf bank_mask:0xf
	v_fmac_f32_dpp v132, -v145, v116 row_newbcast:2 row_mask:0xf bank_mask:0xf
	v_fmac_f32_dpp v133, -v144, v113 row_newbcast:15 row_mask:0xf bank_mask:0xf
	v_fmac_f32_dpp v130, -v145, v118 row_newbcast:4 row_mask:0xf bank_mask:0xf
	v_fmac_f32_dpp v131, -v145, v119 row_newbcast:5 row_mask:0xf bank_mask:0xf
	v_fmac_f32_dpp v132, -v145, v120 row_newbcast:6 row_mask:0xf bank_mask:0xf
	v_fmac_f32_dpp v133, -v145, v117 row_newbcast:3 row_mask:0xf bank_mask:0xf
	v_fmac_f32_dpp v130, -v145, v122 row_newbcast:8 row_mask:0xf bank_mask:0xf
	v_fmac_f32_dpp v131, -v145, v123 row_newbcast:9 row_mask:0xf bank_mask:0xf
	v_fmac_f32_dpp v132, -v145, v124 row_newbcast:10 row_mask:0xf bank_mask:0xf
	v_fmac_f32_dpp v133, -v145, v121 row_newbcast:7 row_mask:0xf bank_mask:0xf
	v_fmac_f32_dpp v130, -v145, v126 row_newbcast:12 row_mask:0xf bank_mask:0xf
	v_fmac_f32_dpp v131, -v145, v127 row_newbcast:13 row_mask:0xf bank_mask:0xf
	v_fmac_f32_dpp v132, -v145, v128 row_newbcast:14 row_mask:0xf bank_mask:0xf
	v_fmac_f32_dpp v133, -v145, v125 row_newbcast:11 row_mask:0xf bank_mask:0xf
	s_nop 1
	v_fmac_f32_dpp v133, -v145, v129 row_newbcast:15 row_mask:0xf bank_mask:0xf
	v_cndmask_b32_e64 v134, 0, 1.0, vcc
	v_add_f32_e32 v20, v130, v131
	v_add_f32_e32 v21, v132, v133
	v_add_f32_e32 v100, v20, v21
	s_waitcnt lgkmcnt(2)
	v_cmp_eq_u32_e32 vcc, 32, v139
	v_mul_f32_dpp v137, -v140, v101 row_newbcast:3 row_mask:0xf bank_mask:0xf
	v_fmac_f32_dpp v134, -v140, v102 row_newbcast:4 row_mask:0xf bank_mask:0xf
	v_mul_f32_dpp v135, -v140, v103 row_newbcast:5 row_mask:0xf bank_mask:0xf
	v_mul_f32_dpp v136, -v140, v100 row_newbcast:2 row_mask:0xf bank_mask:0xf
	v_fmac_f32_dpp v137, -v140, v105 row_newbcast:7 row_mask:0xf bank_mask:0xf
	v_fmac_f32_dpp v134, -v140, v106 row_newbcast:8 row_mask:0xf bank_mask:0xf
	v_fmac_f32_dpp v135, -v140, v107 row_newbcast:9 row_mask:0xf bank_mask:0xf
	v_fmac_f32_dpp v136, -v140, v104 row_newbcast:6 row_mask:0xf bank_mask:0xf
	v_fmac_f32_dpp v137, -v140, v109 row_newbcast:11 row_mask:0xf bank_mask:0xf
	v_fmac_f32_dpp v134, -v140, v110 row_newbcast:12 row_mask:0xf bank_mask:0xf
	v_fmac_f32_dpp v135, -v140, v111 row_newbcast:13 row_mask:0xf bank_mask:0xf
	v_fmac_f32_dpp v136, -v140, v108 row_newbcast:10 row_mask:0xf bank_mask:0xf
	v_fmac_f32_dpp v137, -v140, v113 row_newbcast:15 row_mask:0xf bank_mask:0xf
	v_fmac_f32_dpp v134, -v141, v114 row_newbcast:0 row_mask:0xf bank_mask:0xf
	v_fmac_f32_dpp v135, -v141, v115 row_newbcast:1 row_mask:0xf bank_mask:0xf
	v_fmac_f32_dpp v136, -v140, v112 row_newbcast:14 row_mask:0xf bank_mask:0xf
	v_fmac_f32_dpp v137, -v141, v117 row_newbcast:3 row_mask:0xf bank_mask:0xf
	v_fmac_f32_dpp v134, -v141, v118 row_newbcast:4 row_mask:0xf bank_mask:0xf
	v_fmac_f32_dpp v135, -v141, v119 row_newbcast:5 row_mask:0xf bank_mask:0xf
	v_fmac_f32_dpp v136, -v141, v116 row_newbcast:2 row_mask:0xf bank_mask:0xf
	v_fmac_f32_dpp v137, -v141, v121 row_newbcast:7 row_mask:0xf bank_mask:0xf
	v_fmac_f32_dpp v134, -v141, v122 row_newbcast:8 row_mask:0xf bank_mask:0xf
	v_fmac_f32_dpp v135, -v141, v123 row_newbcast:9 row_mask:0xf bank_mask:0xf
	v_fmac_f32_dpp v136, -v141, v120 row_newbcast:6 row_mask:0xf bank_mask:0xf
	v_fmac_f32_dpp v137, -v141, v125 row_newbcast:11 row_mask:0xf bank_mask:0xf
	v_fmac_f32_dpp v134, -v141, v126 row_newbcast:12 row_mask:0xf bank_mask:0xf
	v_fmac_f32_dpp v135, -v141, v127 row_newbcast:13 row_mask:0xf bank_mask:0xf
	v_fmac_f32_dpp v136, -v141, v124 row_newbcast:10 row_mask:0xf bank_mask:0xf
	v_fmac_f32_dpp v137, -v141, v129 row_newbcast:15 row_mask:0xf bank_mask:0xf
	s_nop 0
	v_fmac_f32_dpp v136, -v141, v128 row_newbcast:14 row_mask:0xf bank_mask:0xf
	v_cndmask_b32_e64 v130, 0, 1.0, vcc
	v_add_f32_e32 v20, v134, v135
	v_add_f32_e32 v21, v136, v137
	v_add_f32_e32 v99, v20, v21
	s_waitcnt lgkmcnt(0)
	v_mul_f32_dpp v132, -v148, v100 row_newbcast:2 row_mask:0xf bank_mask:0xf
	v_mul_f32_dpp v133, -v148, v101 row_newbcast:3 row_mask:0xf bank_mask:0xf
	v_fmac_f32_dpp v130, -v148, v102 row_newbcast:4 row_mask:0xf bank_mask:0xf
	v_mul_f32_dpp v131, -v148, v99 row_newbcast:1 row_mask:0xf bank_mask:0xf
	v_fmac_f32_dpp v132, -v148, v104 row_newbcast:6 row_mask:0xf bank_mask:0xf
	v_fmac_f32_dpp v133, -v148, v105 row_newbcast:7 row_mask:0xf bank_mask:0xf
	v_fmac_f32_dpp v130, -v148, v106 row_newbcast:8 row_mask:0xf bank_mask:0xf
	v_fmac_f32_dpp v131, -v148, v103 row_newbcast:5 row_mask:0xf bank_mask:0xf
	v_fmac_f32_dpp v132, -v148, v108 row_newbcast:10 row_mask:0xf bank_mask:0xf
	v_fmac_f32_dpp v133, -v148, v109 row_newbcast:11 row_mask:0xf bank_mask:0xf
	v_fmac_f32_dpp v130, -v148, v110 row_newbcast:12 row_mask:0xf bank_mask:0xf
	v_fmac_f32_dpp v131, -v148, v107 row_newbcast:9 row_mask:0xf bank_mask:0xf
	v_fmac_f32_dpp v132, -v148, v112 row_newbcast:14 row_mask:0xf bank_mask:0xf
	v_fmac_f32_dpp v133, -v148, v113 row_newbcast:15 row_mask:0xf bank_mask:0xf
	v_fmac_f32_dpp v130, -v149, v114 row_newbcast:0 row_mask:0xf bank_mask:0xf
	v_fmac_f32_dpp v131, -v148, v111 row_newbcast:13 row_mask:0xf bank_mask:0xf
	v_fmac_f32_dpp v132, -v149, v116 row_newbcast:2 row_mask:0xf bank_mask:0xf
	v_fmac_f32_dpp v133, -v149, v117 row_newbcast:3 row_mask:0xf bank_mask:0xf
	v_fmac_f32_dpp v130, -v149, v118 row_newbcast:4 row_mask:0xf bank_mask:0xf
	v_fmac_f32_dpp v131, -v149, v115 row_newbcast:1 row_mask:0xf bank_mask:0xf
	v_fmac_f32_dpp v132, -v149, v120 row_newbcast:6 row_mask:0xf bank_mask:0xf
	v_fmac_f32_dpp v133, -v149, v121 row_newbcast:7 row_mask:0xf bank_mask:0xf
	v_fmac_f32_dpp v130, -v149, v122 row_newbcast:8 row_mask:0xf bank_mask:0xf
	v_fmac_f32_dpp v131, -v149, v119 row_newbcast:5 row_mask:0xf bank_mask:0xf
	v_fmac_f32_dpp v132, -v149, v124 row_newbcast:10 row_mask:0xf bank_mask:0xf
	v_fmac_f32_dpp v133, -v149, v125 row_newbcast:11 row_mask:0xf bank_mask:0xf
	v_fmac_f32_dpp v130, -v149, v126 row_newbcast:12 row_mask:0xf bank_mask:0xf
	v_fmac_f32_dpp v131, -v149, v123 row_newbcast:9 row_mask:0xf bank_mask:0xf
	v_fmac_f32_dpp v132, -v149, v128 row_newbcast:14 row_mask:0xf bank_mask:0xf
	v_fmac_f32_dpp v133, -v149, v129 row_newbcast:15 row_mask:0xf bank_mask:0xf
	v_fmac_f32_dpp v131, -v149, v127 row_newbcast:13 row_mask:0xf bank_mask:0xf
	v_add_f32_e32 v20, v130, v131
	v_add_f32_e32 v21, v132, v133
	v_add_f32_e32 v98, v20, v21
	v_cndmask_b32_e64 v176, -v98, -v99, s[2:3]
	v_cndmask_b32_e64 v177, -v100, -v101, s[2:3]
	v_cndmask_b32_e64 v178, -v102, -v103, s[2:3]
	v_cndmask_b32_e64 v179, -v104, -v105, s[2:3]
	v_cndmask_b32_e64 v180, -v106, -v107, s[2:3]
	v_cndmask_b32_e64 v181, -v108, -v109, s[2:3]
	v_cndmask_b32_e64 v182, -v110, -v111, s[2:3]
	v_cndmask_b32_e64 v183, -v112, -v113, s[2:3]
	v_cndmask_b32_e64 v242, -v114, -v115, s[2:3]
	v_cndmask_b32_e64 v243, -v116, -v117, s[2:3]
	v_cndmask_b32_e64 v244, -v118, -v119, s[2:3]
	v_cndmask_b32_e64 v245, -v120, -v121, s[2:3]
	v_cndmask_b32_e64 v246, -v122, -v123, s[2:3]
	v_cndmask_b32_e64 v247, -v124, -v125, s[2:3]
	v_cndmask_b32_e64 v156, -v126, -v127, s[2:3]
	v_cndmask_b32_e64 v157, -v128, -v129, s[2:3]
	s_waitcnt lgkmcnt(0)
	s_nop 1
	v_mfma_f32_32x32x2_f32 v[2:17], v226, v176, 0
	v_mfma_f32_32x32x2_f32 v[2:17], v227, v177, v[2:17]
	v_mfma_f32_32x32x2_f32 v[2:17], v228, v178, v[2:17]
	v_mfma_f32_32x32x2_f32 v[2:17], v229, v179, v[2:17]
	v_mfma_f32_32x32x2_f32 v[2:17], v230, v180, v[2:17]
	v_mfma_f32_32x32x2_f32 v[2:17], v231, v181, v[2:17]
	v_mfma_f32_32x32x2_f32 v[2:17], v232, v182, v[2:17]
	v_mfma_f32_32x32x2_f32 v[2:17], v233, v183, v[2:17]
	v_mfma_f32_32x32x2_f32 v[2:17], v234, v242, v[2:17]
	v_mfma_f32_32x32x2_f32 v[2:17], v235, v243, v[2:17]
	v_mfma_f32_32x32x2_f32 v[2:17], v236, v244, v[2:17]
	v_mfma_f32_32x32x2_f32 v[2:17], v237, v245, v[2:17]
	v_mfma_f32_32x32x2_f32 v[2:17], v238, v246, v[2:17]
	v_mfma_f32_32x32x2_f32 v[2:17], v239, v247, v[2:17]
	v_mfma_f32_32x32x2_f32 v[2:17], v240, v156, v[2:17]
	v_mfma_f32_32x32x2_f32 v[2:17], v241, v157, v[2:17]
	v_cmp_eq_u32_e32 vcc, 0, v153
	s_nop 1
	v_cndmask_b32_e64 v160, 0, 1.0, vcc
	v_cmp_eq_u32_e32 vcc, 1, v153
	s_nop 1
	v_cndmask_b32_e64 v161, 0, 1.0, vcc
	v_cmp_eq_u32_e32 vcc, 2, v153
	s_nop 1
	v_cndmask_b32_e64 v162, 0, 1.0, vcc
	v_cmp_eq_u32_e32 vcc, 3, v153
	s_nop 1
	v_cndmask_b32_e64 v163, 0, 1.0, vcc
	v_cmp_eq_u32_e32 vcc, 8, v153
	s_nop 1
	v_cndmask_b32_e64 v164, 0, 1.0, vcc
	v_cmp_eq_u32_e32 vcc, 9, v153
	s_nop 1
	v_cndmask_b32_e64 v165, 0, 1.0, vcc
	v_cmp_eq_u32_e32 vcc, 10, v153
	s_nop 1
	v_cndmask_b32_e64 v166, 0, 1.0, vcc
	v_cmp_eq_u32_e32 vcc, 11, v153
	s_nop 1
	v_cndmask_b32_e64 v167, 0, 1.0, vcc
	v_cmp_eq_u32_e32 vcc, 16, v153
	s_nop 1
	v_cndmask_b32_e64 v168, 0, 1.0, vcc
	v_cmp_eq_u32_e32 vcc, 17, v153
	s_nop 1
	v_cndmask_b32_e64 v169, 0, 1.0, vcc
	v_cmp_eq_u32_e32 vcc, 18, v153
	s_nop 1
	v_cndmask_b32_e64 v170, 0, 1.0, vcc
	v_cmp_eq_u32_e32 vcc, 19, v153
	s_nop 1
	v_cndmask_b32_e64 v171, 0, 1.0, vcc
	v_cmp_eq_u32_e32 vcc, 24, v153
	s_nop 1
	v_cndmask_b32_e64 v172, 0, 1.0, vcc
	v_cmp_eq_u32_e32 vcc, 25, v153
	s_nop 1
	v_cndmask_b32_e64 v173, 0, 1.0, vcc
	v_cmp_eq_u32_e32 vcc, 26, v153
	s_nop 1
	v_cndmask_b32_e64 v174, 0, 1.0, vcc
	v_cmp_eq_u32_e32 vcc, 27, v153
	s_nop 1
	v_cndmask_b32_e64 v175, 0, 1.0, vcc
	v_permlane32_swap_b32_e32 v160, v2
	v_permlane32_swap_b32_e32 v161, v3
	v_permlane32_swap_b32_e32 v162, v4
	v_permlane32_swap_b32_e32 v163, v5
	v_permlane32_swap_b32_e32 v164, v6
	v_permlane32_swap_b32_e32 v165, v7
	v_permlane32_swap_b32_e32 v166, v8
	v_permlane32_swap_b32_e32 v167, v9
	v_permlane32_swap_b32_e32 v168, v10
	v_permlane32_swap_b32_e32 v169, v11
	v_permlane32_swap_b32_e32 v170, v12
	v_permlane32_swap_b32_e32 v171, v13
	v_permlane32_swap_b32_e32 v172, v14
	v_permlane32_swap_b32_e32 v173, v15
	v_permlane32_swap_b32_e32 v174, v16
	v_permlane32_swap_b32_e32 v175, v17
	ds_read_b32 v140, v138 offset:6000
	ds_read_b32 v148, v138 offset:5856
	s_waitcnt lgkmcnt(2)
	v_mov_b32_e32 v97, v17
	ds_read_b32 v144, v138 offset:5712
	s_waitcnt lgkmcnt(2)
	v_mul_f32_dpp v133, -v140, v97 row_newbcast:3 row_mask:0xf bank_mask:0xf
	v_add_f32_e32 v96, v16, v133
	ds_read_b32 v140, v138 offset:5568
	s_waitcnt lgkmcnt(2)
	v_mul_f32_dpp v137, -v148, v97 row_newbcast:3 row_mask:0xf bank_mask:0xf
	v_mul_f32_dpp v136, -v148, v96 row_newbcast:2 row_mask:0xf bank_mask:0xf
	v_add_f32_e32 v21, v136, v137
	v_add_f32_e32 v95, v15, v21
	ds_read_b32 v148, v138 offset:5408
	s_waitcnt lgkmcnt(2)
	v_mul_f32_dpp v132, -v144, v96 row_newbcast:2 row_mask:0xf bank_mask:0xf
	v_mul_f32_dpp v133, -v144, v97 row_newbcast:3 row_mask:0xf bank_mask:0xf
	v_mul_f32_dpp v131, -v144, v95 row_newbcast:1 row_mask:0xf bank_mask:0xf
	v_add_f32_e32 v20, v14, v131
	v_add_f32_e32 v21, v132, v133
	v_add_f32_e32 v94, v20, v21
	ds_read_b32 v144, v138 offset:5248
	s_waitcnt lgkmcnt(2)
	v_mul_f32_dpp v135, -v140, v95 row_newbcast:1 row_mask:0xf bank_mask:0xf
	v_mul_f32_dpp v136, -v140, v96 row_newbcast:2 row_mask:0xf bank_mask:0xf
	v_mul_f32_dpp v137, -v140, v97 row_newbcast:3 row_mask:0xf bank_mask:0xf
	v_fmac_f32_dpp v175, -v140, v94 row_newbcast:0 row_mask:0xf bank_mask:0xf
	v_add_f32_e32 v20, v175, v135
	v_add_f32_e32 v21, v136, v137
	v_add_f32_e32 v93, v20, v21
	ds_read_b32 v140, v138 offset:5088
	s_waitcnt lgkmcnt(2)
	v_fmac_f32_dpp v174, -v148, v94 row_newbcast:4 row_mask:0xf bank_mask:0xf
	v_mul_f32_dpp v131, -v148, v95 row_newbcast:5 row_mask:0xf bank_mask:0xf
	v_mul_f32_dpp v132, -v148, v96 row_newbcast:6 row_mask:0xf bank_mask:0xf
	v_mul_f32_dpp v133, -v148, v93 row_newbcast:3 row_mask:0xf bank_mask:0xf
	s_nop 1
	v_fmac_f32_dpp v133, -v148, v97 row_newbcast:7 row_mask:0xf bank_mask:0xf
	v_add_f32_e32 v20, v174, v131
	v_add_f32_e32 v21, v132, v133
	v_add_f32_e32 v92, v20, v21
	ds_read_b32 v148, v138 offset:4928
	s_waitcnt lgkmcnt(2)
	v_mul_f32_dpp v137, -v144, v93 row_newbcast:3 row_mask:0xf bank_mask:0xf
	v_fmac_f32_dpp v173, -v144, v94 row_newbcast:4 row_mask:0xf bank_mask:0xf
	v_mul_f32_dpp v135, -v144, v95 row_newbcast:5 row_mask:0xf bank_mask:0xf
	v_mul_f32_dpp v136, -v144, v92 row_newbcast:2 row_mask:0xf bank_mask:0xf
	v_fmac_f32_dpp v137, -v144, v97 row_newbcast:7 row_mask:0xf bank_mask:0xf
	s_nop 0
	v_fmac_f32_dpp v136, -v144, v96 row_newbcast:6 row_mask:0xf bank_mask:0xf
	v_add_f32_e32 v20, v173, v135
	v_add_f32_e32 v21, v136, v137
	v_add_f32_e32 v91, v20, v21
	ds_read_b32 v144, v138 offset:4752
	s_waitcnt lgkmcnt(2)
	v_mul_f32_dpp v132, -v140, v92 row_newbcast:2 row_mask:0xf bank_mask:0xf
	v_mul_f32_dpp v133, -v140, v93 row_newbcast:3 row_mask:0xf bank_mask:0xf
	v_fmac_f32_dpp v172, -v140, v94 row_newbcast:4 row_mask:0xf bank_mask:0xf
	v_mul_f32_dpp v131, -v140, v91 row_newbcast:1 row_mask:0xf bank_mask:0xf
	v_fmac_f32_dpp v132, -v140, v96 row_newbcast:6 row_mask:0xf bank_mask:0xf
	v_fmac_f32_dpp v133, -v140, v97 row_newbcast:7 row_mask:0xf bank_mask:0xf
	v_fmac_f32_dpp v131, -v140, v95 row_newbcast:5 row_mask:0xf bank_mask:0xf
	v_add_f32_e32 v20, v172, v131
	v_add_f32_e32 v21, v132, v133
	v_add_f32_e32 v90, v20, v21
	ds_read_b32 v140, v138 offset:4576
	s_waitcnt lgkmcnt(2)
	v_mul_f32_dpp v135, -v148, v91 row_newbcast:1 row_mask:0xf bank_mask:0xf
	v_mul_f32_dpp v136, -v148, v92 row_newbcast:2 row_mask:0xf bank_mask:0xf
	v_mul_f32_dpp v137, -v148, v93 row_newbcast:3 row_mask:0xf bank_mask:0xf
	v_fmac_f32_dpp v13, -v148, v90 row_newbcast:0 row_mask:0xf bank_mask:0xf
	v_fmac_f32_dpp v135, -v148, v95 row_newbcast:5 row_mask:0xf bank_mask:0xf
	v_fmac_f32_dpp v136, -v148, v96 row_newbcast:6 row_mask:0xf bank_mask:0xf
	v_fmac_f32_dpp v137, -v148, v97 row_newbcast:7 row_mask:0xf bank_mask:0xf
	v_fmac_f32_dpp v13, -v148, v94 row_newbcast:4 row_mask:0xf bank_mask:0xf
	v_add_f32_e32 v20, v13, v135
	v_add_f32_e32 v21, v136, v137
	v_add_f32_e32 v89, v20, v21
	ds_read_b32 v148, v138 offset:4400
	s_waitcnt lgkmcnt(2)
	v_fmac_f32_dpp v12, -v144, v90 row_newbcast:4 row_mask:0xf bank_mask:0xf
	v_mul_f32_dpp v131, -v144, v91 row_newbcast:5 row_mask:0xf bank_mask:0xf
	v_mul_f32_dpp v132, -v144, v92 row_newbcast:6 row_mask:0xf bank_mask:0xf
	v_mul_f32_dpp v133, -v144, v89 row_newbcast:3 row_mask:0xf bank_mask:0xf
	v_fmac_f32_dpp v12, -v144, v94 row_newbcast:8 row_mask:0xf bank_mask:0xf
	v_fmac_f32_dpp v131, -v144, v95 row_newbcast:9 row_mask:0xf bank_mask:0xf
	v_fmac_f32_dpp v132, -v144, v96 row_newbcast:10 row_mask:0xf bank_mask:0xf
	v_fmac_f32_dpp v133, -v144, v93 row_newbcast:7 row_mask:0xf bank_mask:0xf
	s_nop 1
	v_fmac_f32_dpp v133, -v144, v97 row_newbcast:11 row_mask:0xf bank_mask:0xf
	v_add_f32_e32 v20, v12, v131
	v_add_f32_e32 v21, v132, v133
	v_add_f32_e32 v88, v20, v21
	ds_read_b32 v144, v138 offset:4224
	s_waitcnt lgkmcnt(2)
	v_mul_f32_dpp v137, -v140, v89 row_newbcast:3 row_mask:0xf bank_mask:0xf
	v_fmac_f32_dpp v11, -v140, v90 row_newbcast:4 row_mask:0xf bank_mask:0xf
	v_mul_f32_dpp v135, -v140, v91 row_newbcast:5 row_mask:0xf bank_mask:0xf
	v_mul_f32_dpp v136, -v140, v88 row_newbcast:2 row_mask:0xf bank_mask:0xf
	v_fmac_f32_dpp v137, -v140, v93 row_newbcast:7 row_mask:0xf bank_mask:0xf
	v_fmac_f32_dpp v11, -v140, v94 row_newbcast:8 row_mask:0xf bank_mask:0xf
	v_fmac_f32_dpp v135, -v140, v95 row_newbcast:9 row_mask:0xf bank_mask:0xf
	v_fmac_f32_dpp v136, -v140, v92 row_newbcast:6 row_mask:0xf bank_mask:0xf
	v_fmac_f32_dpp v137, -v140, v97 row_newbcast:11 row_mask:0xf bank_mask:0xf
	s_nop 0
	v_fmac_f32_dpp v136, -v140, v96 row_newbcast:10 row_mask:0xf bank_mask:0xf
	v_add_f32_e32 v20, v11, v135
	v_add_f32_e32 v21, v136, v137
	v_add_f32_e32 v87, v20, v21
	ds_read_b32 v140, v138 offset:4032
	s_waitcnt lgkmcnt(2)
	v_mul_f32_dpp v132, -v148, v88 row_newbcast:2 row_mask:0xf bank_mask:0xf
	v_mul_f32_dpp v133, -v148, v89 row_newbcast:3 row_mask:0xf bank_mask:0xf
	v_fmac_f32_dpp v10, -v148, v90 row_newbcast:4 row_mask:0xf bank_mask:0xf
	v_mul_f32_dpp v131, -v148, v87 row_newbcast:1 row_mask:0xf bank_mask:0xf
	v_fmac_f32_dpp v132, -v148, v92 row_newbcast:6 row_mask:0xf bank_mask:0xf
	v_fmac_f32_dpp v133, -v148, v93 row_newbcast:7 row_mask:0xf bank_mask:0xf
	v_fmac_f32_dpp v10, -v148, v94 row_newbcast:8 row_mask:0xf bank_mask:0xf
	v_fmac_f32_dpp v131, -v148, v91 row_newbcast:5 row_mask:0xf bank_mask:0xf
	v_fmac_f32_dpp v132, -v148, v96 row_newbcast:10 row_mask:0xf bank_mask:0xf
	v_fmac_f32_dpp v133, -v148, v97 row_newbcast:11 row_mask:0xf bank_mask:0xf
	v_fmac_f32_dpp v131, -v148, v95 row_newbcast:9 row_mask:0xf bank_mask:0xf
	v_add_f32_e32 v20, v10, v131
	v_add_f32_e32 v21, v132, v133
	v_add_f32_e32 v86, v20, v21
	ds_read_b32 v148, v138 offset:3840
	s_waitcnt lgkmcnt(2)
	v_mul_f32_dpp v135, -v144, v87 row_newbcast:1 row_mask:0xf bank_mask:0xf
	v_mul_f32_dpp v136, -v144, v88 row_newbcast:2 row_mask:0xf bank_mask:0xf
	v_mul_f32_dpp v137, -v144, v89 row_newbcast:3 row_mask:0xf bank_mask:0xf
	v_fmac_f32_dpp v171, -v144, v86 row_newbcast:0 row_mask:0xf bank_mask:0xf
	v_fmac_f32_dpp v135, -v144, v91 row_newbcast:5 row_mask:0xf bank_mask:0xf
	v_fmac_f32_dpp v136, -v144, v92 row_newbcast:6 row_mask:0xf bank_mask:0xf
	v_fmac_f32_dpp v137, -v144, v93 row_newbcast:7 row_mask:0xf bank_mask:0xf
	v_fmac_f32_dpp v171, -v144, v90 row_newbcast:4 row_mask:0xf bank_mask:0xf
	v_fmac_f32_dpp v135, -v144, v95 row_newbcast:9 row_mask:0xf bank_mask:0xf
	v_fmac_f32_dpp v136, -v144, v96 row_newbcast:10 row_mask:0xf bank_mask:0xf
	v_fmac_f32_dpp v137, -v144, v97 row_newbcast:11 row_mask:0xf bank_mask:0xf
	v_fmac_f32_dpp v171, -v144, v94 row_newbcast:8 row_mask:0xf bank_mask:0xf
	v_add_f32_e32 v20, v171, v135
	v_add_f32_e32 v21, v136, v137
	v_add_f32_e32 v85, v20, v21
	ds_read_b32 v144, v138 offset:3648
	s_waitcnt lgkmcnt(2)
	v_fmac_f32_dpp v170, -v140, v86 row_newbcast:4 row_mask:0xf bank_mask:0xf
	v_mul_f32_dpp v131, -v140, v87 row_newbcast:5 row_mask:0xf bank_mask:0xf
	v_mul_f32_dpp v132, -v140, v88 row_newbcast:6 row_mask:0xf bank_mask:0xf
	v_mul_f32_dpp v133, -v140, v85 row_newbcast:3 row_mask:0xf bank_mask:0xf
	v_fmac_f32_dpp v170, -v140, v90 row_newbcast:8 row_mask:0xf bank_mask:0xf
	v_fmac_f32_dpp v131, -v140, v91 row_newbcast:9 row_mask:0xf bank_mask:0xf
	v_fmac_f32_dpp v132, -v140, v92 row_newbcast:10 row_mask:0xf bank_mask:0xf
	v_fmac_f32_dpp v133, -v140, v89 row_newbcast:7 row_mask:0xf bank_mask:0xf
	v_fmac_f32_dpp v170, -v140, v94 row_newbcast:12 row_mask:0xf bank_mask:0xf
	v_fmac_f32_dpp v131, -v140, v95 row_newbcast:13 row_mask:0xf bank_mask:0xf
	v_fmac_f32_dpp v132, -v140, v96 row_newbcast:14 row_mask:0xf bank_mask:0xf
	v_fmac_f32_dpp v133, -v140, v93 row_newbcast:11 row_mask:0xf bank_mask:0xf
	s_nop 1
	v_fmac_f32_dpp v133, -v140, v97 row_newbcast:15 row_mask:0xf bank_mask:0xf
	v_add_f32_e32 v20, v170, v131
	v_add_f32_e32 v21, v132, v133
	v_add_f32_e32 v84, v20, v21
	ds_read_b32 v140, v138 offset:3456
	s_waitcnt lgkmcnt(2)
	v_mul_f32_dpp v137, -v148, v85 row_newbcast:3 row_mask:0xf bank_mask:0xf
	v_fmac_f32_dpp v169, -v148, v86 row_newbcast:4 row_mask:0xf bank_mask:0xf
	v_mul_f32_dpp v135, -v148, v87 row_newbcast:5 row_mask:0xf bank_mask:0xf
	v_mul_f32_dpp v136, -v148, v84 row_newbcast:2 row_mask:0xf bank_mask:0xf
	v_fmac_f32_dpp v137, -v148, v89 row_newbcast:7 row_mask:0xf bank_mask:0xf
	v_fmac_f32_dpp v169, -v148, v90 row_newbcast:8 row_mask:0xf bank_mask:0xf
	v_fmac_f32_dpp v135, -v148, v91 row_newbcast:9 row_mask:0xf bank_mask:0xf
	v_fmac_f32_dpp v136, -v148, v88 row_newbcast:6 row_mask:0xf bank_mask:0xf
	v_fmac_f32_dpp v137, -v148, v93 row_newbcast:11 row_mask:0xf bank_mask:0xf
	v_fmac_f32_dpp v169, -v148, v94 row_newbcast:12 row_mask:0xf bank_mask:0xf
	v_fmac_f32_dpp v135, -v148, v95 row_newbcast:13 row_mask:0xf bank_mask:0xf
	v_fmac_f32_dpp v136, -v148, v92 row_newbcast:10 row_mask:0xf bank_mask:0xf
	v_fmac_f32_dpp v137, -v148, v97 row_newbcast:15 row_mask:0xf bank_mask:0xf
	s_nop 0
	v_fmac_f32_dpp v136, -v148, v96 row_newbcast:14 row_mask:0xf bank_mask:0xf
	v_add_f32_e32 v20, v169, v135
	v_add_f32_e32 v21, v136, v137
	v_add_f32_e32 v83, v20, v21
	ds_read_b32 v148, v138 offset:3248
	ds_read_b32 v149, v138 offset:3312
	s_waitcnt lgkmcnt(3)
	v_mul_f32_dpp v132, -v144, v84 row_newbcast:2 row_mask:0xf bank_mask:0xf
	v_mul_f32_dpp v133, -v144, v85 row_newbcast:3 row_mask:0xf bank_mask:0xf
	v_fmac_f32_dpp v168, -v144, v86 row_newbcast:4 row_mask:0xf bank_mask:0xf
	v_mul_f32_dpp v131, -v144, v83 row_newbcast:1 row_mask:0xf bank_mask:0xf
	v_fmac_f32_dpp v132, -v144, v88 row_newbcast:6 row_mask:0xf bank_mask:0xf
	v_fmac_f32_dpp v133, -v144, v89 row_newbcast:7 row_mask:0xf bank_mask:0xf
	v_fmac_f32_dpp v168, -v144, v90 row_newbcast:8 row_mask:0xf bank_mask:0xf
	v_fmac_f32_dpp v131, -v144, v87 row_newbcast:5 row_mask:0xf bank_mask:0xf
	v_fmac_f32_dpp v132, -v144, v92 row_newbcast:10 row_mask:0xf bank_mask:0xf
	v_fmac_f32_dpp v133, -v144, v93 row_newbcast:11 row_mask:0xf bank_mask:0xf
	v_fmac_f32_dpp v168, -v144, v94 row_newbcast:12 row_mask:0xf bank_mask:0xf
	v_fmac_f32_dpp v131, -v144, v91 row_newbcast:9 row_mask:0xf bank_mask:0xf
	v_fmac_f32_dpp v132, -v144, v96 row_newbcast:14 row_mask:0xf bank_mask:0xf
	v_fmac_f32_dpp v133, -v144, v97 row_newbcast:15 row_mask:0xf bank_mask:0xf
	v_fmac_f32_dpp v131, -v144, v95 row_newbcast:13 row_mask:0xf bank_mask:0xf
	v_add_f32_e32 v20, v168, v131
	v_add_f32_e32 v21, v132, v133
	v_add_f32_e32 v82, v20, v21
	ds_read_b32 v144, v138 offset:3040
	ds_read_b32 v145, v138 offset:3104
	s_waitcnt lgkmcnt(4)
	v_mul_f32_dpp v135, -v140, v83 row_newbcast:1 row_mask:0xf bank_mask:0xf
	v_mul_f32_dpp v136, -v140, v84 row_newbcast:2 row_mask:0xf bank_mask:0xf
	v_mul_f32_dpp v137, -v140, v85 row_newbcast:3 row_mask:0xf bank_mask:0xf
	v_fmac_f32_dpp v9, -v140, v82 row_newbcast:0 row_mask:0xf bank_mask:0xf
	v_fmac_f32_dpp v135, -v140, v87 row_newbcast:5 row_mask:0xf bank_mask:0xf
	v_fmac_f32_dpp v136, -v140, v88 row_newbcast:6 row_mask:0xf bank_mask:0xf
	v_fmac_f32_dpp v137, -v140, v89 row_newbcast:7 row_mask:0xf bank_mask:0xf
	v_fmac_f32_dpp v9, -v140, v86 row_newbcast:4 row_mask:0xf bank_mask:0xf
	v_fmac_f32_dpp v135, -v140, v91 row_newbcast:9 row_mask:0xf bank_mask:0xf
	v_fmac_f32_dpp v136, -v140, v92 row_newbcast:10 row_mask:0xf bank_mask:0xf
	v_fmac_f32_dpp v137, -v140, v93 row_newbcast:11 row_mask:0xf bank_mask:0xf
	v_fmac_f32_dpp v9, -v140, v90 row_newbcast:8 row_mask:0xf bank_mask:0xf
	v_fmac_f32_dpp v135, -v140, v95 row_newbcast:13 row_mask:0xf bank_mask:0xf
	v_fmac_f32_dpp v136, -v140, v96 row_newbcast:14 row_mask:0xf bank_mask:0xf
	v_fmac_f32_dpp v137, -v140, v97 row_newbcast:15 row_mask:0xf bank_mask:0xf
	v_fmac_f32_dpp v9, -v140, v94 row_newbcast:12 row_mask:0xf bank_mask:0xf
	v_add_f32_e32 v20, v9, v135
	v_add_f32_e32 v21, v136, v137
	v_add_f32_e32 v81, v20, v21
	ds_read_b32 v140, v138 offset:2832
	ds_read_b32 v141, v138 offset:2896
	s_waitcnt lgkmcnt(4)
	v_fmac_f32_dpp v8, -v148, v82 row_newbcast:4 row_mask:0xf bank_mask:0xf
	v_mul_f32_dpp v131, -v148, v83 row_newbcast:5 row_mask:0xf bank_mask:0xf
	v_mul_f32_dpp v132, -v148, v84 row_newbcast:6 row_mask:0xf bank_mask:0xf
	v_mul_f32_dpp v133, -v148, v81 row_newbcast:3 row_mask:0xf bank_mask:0xf
	v_fmac_f32_dpp v8, -v148, v86 row_newbcast:8 row_mask:0xf bank_mask:0xf
	v_fmac_f32_dpp v131, -v148, v87 row_newbcast:9 row_mask:0xf bank_mask:0xf
	v_fmac_f32_dpp v132, -v148, v88 row_newbcast:10 row_mask:0xf bank_mask:0xf
	v_fmac_f32_dpp v133, -v148, v85 row_newbcast:7 row_mask:0xf bank_mask:0xf
	v_fmac_f32_dpp v8, -v148, v90 row_newbcast:12 row_mask:0xf bank_mask:0xf
	v_fmac_f32_dpp v131, -v148, v91 row_newbcast:13 row_mask:0xf bank_mask:0xf
	v_fmac_f32_dpp v132, -v148, v92 row_newbcast:14 row_mask:0xf bank_mask:0xf
	v_fmac_f32_dpp v133, -v148, v89 row_newbcast:11 row_mask:0xf bank_mask:0xf
	v_fmac_f32_dpp v8, -v149, v94 row_newbcast:0 row_mask:0xf bank_mask:0xf
	v_fmac_f32_dpp v131, -v149, v95 row_newbcast:1 row_mask:0xf bank_mask:0xf
	v_fmac_f32_dpp v132, -v149, v96 row_newbcast:2 row_mask:0xf bank_mask:0xf
	v_fmac_f32_dpp v133, -v148, v93 row_newbcast:15 row_mask:0xf bank_mask:0xf
	s_nop 1
	v_fmac_f32_dpp v133, -v149, v97 row_newbcast:3 row_mask:0xf bank_mask:0xf
	v_add_f32_e32 v20, v8, v131
	v_add_f32_e32 v21, v132, v133
	v_add_f32_e32 v80, v20, v21
	ds_read_b32 v148, v138 offset:2624
	ds_read_b32 v149, v138 offset:2688
	s_waitcnt lgkmcnt(4)
	v_mul_f32_dpp v137, -v144, v81 row_newbcast:3 row_mask:0xf bank_mask:0xf
	v_fmac_f32_dpp v7, -v144, v82 row_newbcast:4 row_mask:0xf bank_mask:0xf
	v_mul_f32_dpp v135, -v144, v83 row_newbcast:5 row_mask:0xf bank_mask:0xf
	v_mul_f32_dpp v136, -v144, v80 row_newbcast:2 row_mask:0xf bank_mask:0xf
	v_fmac_f32_dpp v137, -v144, v85 row_newbcast:7 row_mask:0xf bank_mask:0xf
	v_fmac_f32_dpp v7, -v144, v86 row_newbcast:8 row_mask:0xf bank_mask:0xf
	v_fmac_f32_dpp v135, -v144, v87 row_newbcast:9 row_mask:0xf bank_mask:0xf
	v_fmac_f32_dpp v136, -v144, v84 row_newbcast:6 row_mask:0xf bank_mask:0xf
	v_fmac_f32_dpp v137, -v144, v89 row_newbcast:11 row_mask:0xf bank_mask:0xf
	v_fmac_f32_dpp v7, -v144, v90 row_newbcast:12 row_mask:0xf bank_mask:0xf
	v_fmac_f32_dpp v135, -v144, v91 row_newbcast:13 row_mask:0xf bank_mask:0xf
	v_fmac_f32_dpp v136, -v144, v88 row_newbcast:10 row_mask:0xf bank_mask:0xf
	v_fmac_f32_dpp v137, -v144, v93 row_newbcast:15 row_mask:0xf bank_mask:0xf
	v_fmac_f32_dpp v7, -v145, v94 row_newbcast:0 row_mask:0xf bank_mask:0xf
	v_fmac_f32_dpp v135, -v145, v95 row_newbcast:1 row_mask:0xf bank_mask:0xf
	v_fmac_f32_dpp v136, -v144, v92 row_newbcast:14 row_mask:0xf bank_mask:0xf
	v_fmac_f32_dpp v137, -v145, v97 row_newbcast:3 row_mask:0xf bank_mask:0xf
	s_nop 0
	v_fmac_f32_dpp v136, -v145, v96 row_newbcast:2 row_mask:0xf bank_mask:0xf
	v_add_f32_e32 v20, v7, v135
	v_add_f32_e32 v21, v136, v137
	v_add_f32_e32 v79, v20, v21
	ds_read_b32 v144, v138 offset:2400
	ds_read_b32 v145, v138 offset:2464
	s_waitcnt lgkmcnt(4)
	v_mul_f32_dpp v132, -v140, v80 row_newbcast:2 row_mask:0xf bank_mask:0xf
	v_mul_f32_dpp v133, -v140, v81 row_newbcast:3 row_mask:0xf bank_mask:0xf
	v_fmac_f32_dpp v6, -v140, v82 row_newbcast:4 row_mask:0xf bank_mask:0xf
	v_mul_f32_dpp v131, -v140, v79 row_newbcast:1 row_mask:0xf bank_mask:0xf
	v_fmac_f32_dpp v132, -v140, v84 row_newbcast:6 row_mask:0xf bank_mask:0xf
	v_fmac_f32_dpp v133, -v140, v85 row_newbcast:7 row_mask:0xf bank_mask:0xf
	v_fmac_f32_dpp v6, -v140, v86 row_newbcast:8 row_mask:0xf bank_mask:0xf
	v_fmac_f32_dpp v131, -v140, v83 row_newbcast:5 row_mask:0xf bank_mask:0xf
	v_fmac_f32_dpp v132, -v140, v88 row_newbcast:10 row_mask:0xf bank_mask:0xf
	v_fmac_f32_dpp v133, -v140, v89 row_newbcast:11 row_mask:0xf bank_mask:0xf
	v_fmac_f32_dpp v6, -v140, v90 row_newbcast:12 row_mask:0xf bank_mask:0xf
	v_fmac_f32_dpp v131, -v140, v87 row_newbcast:9 row_mask:0xf bank_mask:0xf
	v_fmac_f32_dpp v132, -v140, v92 row_newbcast:14 row_mask:0xf bank_mask:0xf
	v_fmac_f32_dpp v133, -v140, v93 row_newbcast:15 row_mask:0xf bank_mask:0xf
	v_fmac_f32_dpp v6, -v141, v94 row_newbcast:0 row_mask:0xf bank_mask:0xf
	v_fmac_f32_dpp v131, -v140, v91 row_newbcast:13 row_mask:0xf bank_mask:0xf
	v_fmac_f32_dpp v132, -v141, v96 row_newbcast:2 row_mask:0xf bank_mask:0xf
	v_fmac_f32_dpp v133, -v141, v97 row_newbcast:3 row_mask:0xf bank_mask:0xf
	v_fmac_f32_dpp v131, -v141, v95 row_newbcast:1 row_mask:0xf bank_mask:0xf
	v_add_f32_e32 v20, v6, v131
	v_add_f32_e32 v21, v132, v133
	v_add_f32_e32 v78, v20, v21
	ds_read_b32 v140, v138 offset:2176
	ds_read_b32 v141, v138 offset:2240
	s_waitcnt lgkmcnt(4)
	v_mul_f32_dpp v135, -v148, v79 row_newbcast:1 row_mask:0xf bank_mask:0xf
	v_mul_f32_dpp v136, -v148, v80 row_newbcast:2 row_mask:0xf bank_mask:0xf
	v_mul_f32_dpp v137, -v148, v81 row_newbcast:3 row_mask:0xf bank_mask:0xf
	v_fmac_f32_dpp v167, -v148, v78 row_newbcast:0 row_mask:0xf bank_mask:0xf
	v_fmac_f32_dpp v135, -v148, v83 row_newbcast:5 row_mask:0xf bank_mask:0xf
	v_fmac_f32_dpp v136, -v148, v84 row_newbcast:6 row_mask:0xf bank_mask:0xf
	v_fmac_f32_dpp v137, -v148, v85 row_newbcast:7 row_mask:0xf bank_mask:0xf
	v_fmac_f32_dpp v167, -v148, v82 row_newbcast:4 row_mask:0xf bank_mask:0xf
	v_fmac_f32_dpp v135, -v148, v87 row_newbcast:9 row_mask:0xf bank_mask:0xf
	v_fmac_f32_dpp v136, -v148, v88 row_newbcast:10 row_mask:0xf bank_mask:0xf
	v_fmac_f32_dpp v137, -v148, v89 row_newbcast:11 row_mask:0xf bank_mask:0xf
	v_fmac_f32_dpp v167, -v148, v86 row_newbcast:8 row_mask:0xf bank_mask:0xf
	v_fmac_f32_dpp v135, -v148, v91 row_newbcast:13 row_mask:0xf bank_mask:0xf
	v_fmac_f32_dpp v136, -v148, v92 row_newbcast:14 row_mask:0xf bank_mask:0xf
	v_fmac_f32_dpp v137, -v148, v93 row_newbcast:15 row_mask:0xf bank_mask:0xf
	v_fmac_f32_dpp v167, -v148, v90 row_newbcast:12 row_mask:0xf bank_mask:0xf
	v_fmac_f32_dpp v135, -v149, v95 row_newbcast:1 row_mask:0xf bank_mask:0xf
	v_fmac_f32_dpp v136, -v149, v96 row_newbcast:2 row_mask:0xf bank_mask:0xf
	v_fmac_f32_dpp v137, -v149, v97 row_newbcast:3 row_mask:0xf bank_mask:0xf
	v_fmac_f32_dpp v167, -v149, v94 row_newbcast:0 row_mask:0xf bank_mask:0xf
	v_add_f32_e32 v20, v167, v135
	v_add_f32_e32 v21, v136, v137
	v_add_f32_e32 v77, v20, v21
	ds_read_b32 v148, v138 offset:1952
	ds_read_b32 v149, v138 offset:2016
	s_waitcnt lgkmcnt(4)
	v_fmac_f32_dpp v166, -v144, v78 row_newbcast:4 row_mask:0xf bank_mask:0xf
	v_mul_f32_dpp v131, -v144, v79 row_newbcast:5 row_mask:0xf bank_mask:0xf
	v_mul_f32_dpp v132, -v144, v80 row_newbcast:6 row_mask:0xf bank_mask:0xf
	v_mul_f32_dpp v133, -v144, v77 row_newbcast:3 row_mask:0xf bank_mask:0xf
	v_fmac_f32_dpp v166, -v144, v82 row_newbcast:8 row_mask:0xf bank_mask:0xf
	v_fmac_f32_dpp v131, -v144, v83 row_newbcast:9 row_mask:0xf bank_mask:0xf
	v_fmac_f32_dpp v132, -v144, v84 row_newbcast:10 row_mask:0xf bank_mask:0xf
	v_fmac_f32_dpp v133, -v144, v81 row_newbcast:7 row_mask:0xf bank_mask:0xf
	v_fmac_f32_dpp v166, -v144, v86 row_newbcast:12 row_mask:0xf bank_mask:0xf
	v_fmac_f32_dpp v131, -v144, v87 row_newbcast:13 row_mask:0xf bank_mask:0xf
	v_fmac_f32_dpp v132, -v144, v88 row_newbcast:14 row_mask:0xf bank_mask:0xf
	v_fmac_f32_dpp v133, -v144, v85 row_newbcast:11 row_mask:0xf bank_mask:0xf
	v_fmac_f32_dpp v166, -v145, v90 row_newbcast:0 row_mask:0xf bank_mask:0xf
	v_fmac_f32_dpp v131, -v145, v91 row_newbcast:1 row_mask:0xf bank_mask:0xf
	v_fmac_f32_dpp v132, -v145, v92 row_newbcast:2 row_mask:0xf bank_mask:0xf
	v_fmac_f32_dpp v133, -v144, v89 row_newbcast:15 row_mask:0xf bank_mask:0xf
	v_fmac_f32_dpp v166, -v145, v94 row_newbcast:4 row_mask:0xf bank_mask:0xf
	v_fmac_f32_dpp v131, -v145, v95 row_newbcast:5 row_mask:0xf bank_mask:0xf
	v_fmac_f32_dpp v132, -v145, v96 row_newbcast:6 row_mask:0xf bank_mask:0xf
	v_fmac_f32_dpp v133, -v145, v93 row_newbcast:3 row_mask:0xf bank_mask:0xf
	s_nop 1
	v_fmac_f32_dpp v133, -v145, v97 row_newbcast:7 row_mask:0xf bank_mask:0xf
	v_add_f32_e32 v20, v166, v131
	v_add_f32_e32 v21, v132, v133
	v_add_f32_e32 v76, v20, v21
	ds_read_b32 v144, v138 offset:1728
	ds_read_b32 v145, v138 offset:1792
	s_waitcnt lgkmcnt(4)
	v_mul_f32_dpp v137, -v140, v77 row_newbcast:3 row_mask:0xf bank_mask:0xf
	v_fmac_f32_dpp v165, -v140, v78 row_newbcast:4 row_mask:0xf bank_mask:0xf
	v_mul_f32_dpp v135, -v140, v79 row_newbcast:5 row_mask:0xf bank_mask:0xf
	v_mul_f32_dpp v136, -v140, v76 row_newbcast:2 row_mask:0xf bank_mask:0xf
	v_fmac_f32_dpp v137, -v140, v81 row_newbcast:7 row_mask:0xf bank_mask:0xf
	v_fmac_f32_dpp v165, -v140, v82 row_newbcast:8 row_mask:0xf bank_mask:0xf
	v_fmac_f32_dpp v135, -v140, v83 row_newbcast:9 row_mask:0xf bank_mask:0xf
	v_fmac_f32_dpp v136, -v140, v80 row_newbcast:6 row_mask:0xf bank_mask:0xf
	v_fmac_f32_dpp v137, -v140, v85 row_newbcast:11 row_mask:0xf bank_mask:0xf
	v_fmac_f32_dpp v165, -v140, v86 row_newbcast:12 row_mask:0xf bank_mask:0xf
	v_fmac_f32_dpp v135, -v140, v87 row_newbcast:13 row_mask:0xf bank_mask:0xf
	v_fmac_f32_dpp v136, -v140, v84 row_newbcast:10 row_mask:0xf bank_mask:0xf
	v_fmac_f32_dpp v137, -v140, v89 row_newbcast:15 row_mask:0xf bank_mask:0xf
	v_fmac_f32_dpp v165, -v141, v90 row_newbcast:0 row_mask:0xf bank_mask:0xf
	v_fmac_f32_dpp v135, -v141, v91 row_newbcast:1 row_mask:0xf bank_mask:0xf
	v_fmac_f32_dpp v136, -v140, v88 row_newbcast:14 row_mask:0xf bank_mask:0xf
	v_fmac_f32_dpp v137, -v141, v93 row_newbcast:3 row_mask:0xf bank_mask:0xf
	v_fmac_f32_dpp v165, -v141, v94 row_newbcast:4 row_mask:0xf bank_mask:0xf
	v_fmac_f32_dpp v135, -v141, v95 row_newbcast:5 row_mask:0xf bank_mask:0xf
	v_fmac_f32_dpp v136, -v141, v92 row_newbcast:2 row_mask:0xf bank_mask:0xf
	v_fmac_f32_dpp v137, -v141, v97 row_newbcast:7 row_mask:0xf bank_mask:0xf
	s_nop 0
	v_fmac_f32_dpp v136, -v141, v96 row_newbcast:6 row_mask:0xf bank_mask:0xf
	v_add_f32_e32 v20, v165, v135
	v_add_f32_e32 v21, v136, v137
	v_add_f32_e32 v75, v20, v21
	ds_read_b32 v140, v138 offset:1488
	ds_read_b32 v141, v138 offset:1552
	s_waitcnt lgkmcnt(4)
	v_mul_f32_dpp v132, -v148, v76 row_newbcast:2 row_mask:0xf bank_mask:0xf
	v_mul_f32_dpp v133, -v148, v77 row_newbcast:3 row_mask:0xf bank_mask:0xf
	v_fmac_f32_dpp v164, -v148, v78 row_newbcast:4 row_mask:0xf bank_mask:0xf
	v_mul_f32_dpp v131, -v148, v75 row_newbcast:1 row_mask:0xf bank_mask:0xf
	v_fmac_f32_dpp v132, -v148, v80 row_newbcast:6 row_mask:0xf bank_mask:0xf
	v_fmac_f32_dpp v133, -v148, v81 row_newbcast:7 row_mask:0xf bank_mask:0xf
	v_fmac_f32_dpp v164, -v148, v82 row_newbcast:8 row_mask:0xf bank_mask:0xf
	v_fmac_f32_dpp v131, -v148, v79 row_newbcast:5 row_mask:0xf bank_mask:0xf
	v_fmac_f32_dpp v132, -v148, v84 row_newbcast:10 row_mask:0xf bank_mask:0xf
	v_fmac_f32_dpp v133, -v148, v85 row_newbcast:11 row_mask:0xf bank_mask:0xf
	v_fmac_f32_dpp v164, -v148, v86 row_newbcast:12 row_mask:0xf bank_mask:0xf
	v_fmac_f32_dpp v131, -v148, v83 row_newbcast:9 row_mask:0xf bank_mask:0xf
	v_fmac_f32_dpp v132, -v148, v88 row_newbcast:14 row_mask:0xf bank_mask:0xf
	v_fmac_f32_dpp v133, -v148, v89 row_newbcast:15 row_mask:0xf bank_mask:0xf
	v_fmac_f32_dpp v164, -v149, v90 row_newbcast:0 row_mask:0xf bank_mask:0xf
	v_fmac_f32_dpp v131, -v148, v87 row_newbcast:13 row_mask:0xf bank_mask:0xf
	v_fmac_f32_dpp v132, -v149, v92 row_newbcast:2 row_mask:0xf bank_mask:0xf
	v_fmac_f32_dpp v133, -v149, v93 row_newbcast:3 row_mask:0xf bank_mask:0xf
	v_fmac_f32_dpp v164, -v149, v94 row_newbcast:4 row_mask:0xf bank_mask:0xf
	v_fmac_f32_dpp v131, -v149, v91 row_newbcast:1 row_mask:0xf bank_mask:0xf
	v_fmac_f32_dpp v132, -v149, v96 row_newbcast:6 row_mask:0xf bank_mask:0xf
	v_fmac_f32_dpp v133, -v149, v97 row_newbcast:7 row_mask:0xf bank_mask:0xf
	v_fmac_f32_dpp v131, -v149, v95 row_newbcast:5 row_mask:0xf bank_mask:0xf
	v_add_f32_e32 v20, v164, v131
	v_add_f32_e32 v21, v132, v133
	v_add_f32_e32 v74, v20, v21
	ds_read_b32 v148, v138 offset:1248
	ds_read_b32 v149, v138 offset:1312
	s_waitcnt lgkmcnt(4)
	v_mul_f32_dpp v135, -v144, v75 row_newbcast:1 row_mask:0xf bank_mask:0xf
	v_mul_f32_dpp v136, -v144, v76 row_newbcast:2 row_mask:0xf bank_mask:0xf
	v_mul_f32_dpp v137, -v144, v77 row_newbcast:3 row_mask:0xf bank_mask:0xf
	v_fmac_f32_dpp v5, -v144, v74 row_newbcast:0 row_mask:0xf bank_mask:0xf
	v_fmac_f32_dpp v135, -v144, v79 row_newbcast:5 row_mask:0xf bank_mask:0xf
	v_fmac_f32_dpp v136, -v144, v80 row_newbcast:6 row_mask:0xf bank_mask:0xf
	v_fmac_f32_dpp v137, -v144, v81 row_newbcast:7 row_mask:0xf bank_mask:0xf
	v_fmac_f32_dpp v5, -v144, v78 row_newbcast:4 row_mask:0xf bank_mask:0xf
	v_fmac_f32_dpp v135, -v144, v83 row_newbcast:9 row_mask:0xf bank_mask:0xf
	v_fmac_f32_dpp v136, -v144, v84 row_newbcast:10 row_mask:0xf bank_mask:0xf
	v_fmac_f32_dpp v137, -v144, v85 row_newbcast:11 row_mask:0xf bank_mask:0xf
	v_fmac_f32_dpp v5, -v144, v82 row_newbcast:8 row_mask:0xf bank_mask:0xf
	v_fmac_f32_dpp v135, -v144, v87 row_newbcast:13 row_mask:0xf bank_mask:0xf
	v_fmac_f32_dpp v136, -v144, v88 row_newbcast:14 row_mask:0xf bank_mask:0xf
	v_fmac_f32_dpp v137, -v144, v89 row_newbcast:15 row_mask:0xf bank_mask:0xf
	v_fmac_f32_dpp v5, -v144, v86 row_newbcast:12 row_mask:0xf bank_mask:0xf
	v_fmac_f32_dpp v135, -v145, v91 row_newbcast:1 row_mask:0xf bank_mask:0xf
	v_fmac_f32_dpp v136, -v145, v92 row_newbcast:2 row_mask:0xf bank_mask:0xf
	v_fmac_f32_dpp v137, -v145, v93 row_newbcast:3 row_mask:0xf bank_mask:0xf
	v_fmac_f32_dpp v5, -v145, v90 row_newbcast:0 row_mask:0xf bank_mask:0xf
	v_fmac_f32_dpp v135, -v145, v95 row_newbcast:5 row_mask:0xf bank_mask:0xf
	v_fmac_f32_dpp v136, -v145, v96 row_newbcast:6 row_mask:0xf bank_mask:0xf
	v_fmac_f32_dpp v137, -v145, v97 row_newbcast:7 row_mask:0xf bank_mask:0xf
	v_fmac_f32_dpp v5, -v145, v94 row_newbcast:4 row_mask:0xf bank_mask:0xf
	v_add_f32_e32 v20, v5, v135
	v_add_f32_e32 v21, v136, v137
	v_add_f32_e32 v73, v20, v21
	ds_read_b32 v144, v138 offset:1008
	ds_read_b32 v145, v138 offset:1072
	s_waitcnt lgkmcnt(4)
	v_fmac_f32_dpp v4, -v140, v74 row_newbcast:4 row_mask:0xf bank_mask:0xf
	v_mul_f32_dpp v131, -v140, v75 row_newbcast:5 row_mask:0xf bank_mask:0xf
	v_mul_f32_dpp v132, -v140, v76 row_newbcast:6 row_mask:0xf bank_mask:0xf
	v_mul_f32_dpp v133, -v140, v73 row_newbcast:3 row_mask:0xf bank_mask:0xf
	v_fmac_f32_dpp v4, -v140, v78 row_newbcast:8 row_mask:0xf bank_mask:0xf
	v_fmac_f32_dpp v131, -v140, v79 row_newbcast:9 row_mask:0xf bank_mask:0xf
	v_fmac_f32_dpp v132, -v140, v80 row_newbcast:10 row_mask:0xf bank_mask:0xf
	v_fmac_f32_dpp v133, -v140, v77 row_newbcast:7 row_mask:0xf bank_mask:0xf
	v_fmac_f32_dpp v4, -v140, v82 row_newbcast:12 row_mask:0xf bank_mask:0xf
	v_fmac_f32_dpp v131, -v140, v83 row_newbcast:13 row_mask:0xf bank_mask:0xf
	v_fmac_f32_dpp v132, -v140, v84 row_newbcast:14 row_mask:0xf bank_mask:0xf
	v_fmac_f32_dpp v133, -v140, v81 row_newbcast:11 row_mask:0xf bank_mask:0xf
	v_fmac_f32_dpp v4, -v141, v86 row_newbcast:0 row_mask:0xf bank_mask:0xf
	v_fmac_f32_dpp v131, -v141, v87 row_newbcast:1 row_mask:0xf bank_mask:0xf
	v_fmac_f32_dpp v132, -v141, v88 row_newbcast:2 row_mask:0xf bank_mask:0xf
	v_fmac_f32_dpp v133, -v140, v85 row_newbcast:15 row_mask:0xf bank_mask:0xf
	v_fmac_f32_dpp v4, -v141, v90 row_newbcast:4 row_mask:0xf bank_mask:0xf
	v_fmac_f32_dpp v131, -v141, v91 row_newbcast:5 row_mask:0xf bank_mask:0xf
	v_fmac_f32_dpp v132, -v141, v92 row_newbcast:6 row_mask:0xf bank_mask:0xf
	v_fmac_f32_dpp v133, -v141, v89 row_newbcast:3 row_mask:0xf bank_mask:0xf
	v_fmac_f32_dpp v4, -v141, v94 row_newbcast:8 row_mask:0xf bank_mask:0xf
	v_fmac_f32_dpp v131, -v141, v95 row_newbcast:9 row_mask:0xf bank_mask:0xf
	v_fmac_f32_dpp v132, -v141, v96 row_newbcast:10 row_mask:0xf bank_mask:0xf
	v_fmac_f32_dpp v133, -v141, v93 row_newbcast:7 row_mask:0xf bank_mask:0xf
	s_nop 1
	v_fmac_f32_dpp v133, -v141, v97 row_newbcast:11 row_mask:0xf bank_mask:0xf
	v_add_f32_e32 v20, v4, v131
	v_add_f32_e32 v21, v132, v133
	v_add_f32_e32 v72, v20, v21
	ds_read_b32 v140, v138 offset:768
	ds_read_b32 v141, v138 offset:832
	s_waitcnt lgkmcnt(4)
	v_mul_f32_dpp v137, -v148, v73 row_newbcast:3 row_mask:0xf bank_mask:0xf
	v_fmac_f32_dpp v3, -v148, v74 row_newbcast:4 row_mask:0xf bank_mask:0xf
	v_mul_f32_dpp v135, -v148, v75 row_newbcast:5 row_mask:0xf bank_mask:0xf
	v_mul_f32_dpp v136, -v148, v72 row_newbcast:2 row_mask:0xf bank_mask:0xf
	v_fmac_f32_dpp v137, -v148, v77 row_newbcast:7 row_mask:0xf bank_mask:0xf
	v_fmac_f32_dpp v3, -v148, v78 row_newbcast:8 row_mask:0xf bank_mask:0xf
	v_fmac_f32_dpp v135, -v148, v79 row_newbcast:9 row_mask:0xf bank_mask:0xf
	v_fmac_f32_dpp v136, -v148, v76 row_newbcast:6 row_mask:0xf bank_mask:0xf
	v_fmac_f32_dpp v137, -v148, v81 row_newbcast:11 row_mask:0xf bank_mask:0xf
	v_fmac_f32_dpp v3, -v148, v82 row_newbcast:12 row_mask:0xf bank_mask:0xf
	v_fmac_f32_dpp v135, -v148, v83 row_newbcast:13 row_mask:0xf bank_mask:0xf
	v_fmac_f32_dpp v136, -v148, v80 row_newbcast:10 row_mask:0xf bank_mask:0xf
	v_fmac_f32_dpp v137, -v148, v85 row_newbcast:15 row_mask:0xf bank_mask:0xf
	v_fmac_f32_dpp v3, -v149, v86 row_newbcast:0 row_mask:0xf bank_mask:0xf
	v_fmac_f32_dpp v135, -v149, v87 row_newbcast:1 row_mask:0xf bank_mask:0xf
	v_fmac_f32_dpp v136, -v148, v84 row_newbcast:14 row_mask:0xf bank_mask:0xf
	v_fmac_f32_dpp v137, -v149, v89 row_newbcast:3 row_mask:0xf bank_mask:0xf
	v_fmac_f32_dpp v3, -v149, v90 row_newbcast:4 row_mask:0xf bank_mask:0xf
	v_fmac_f32_dpp v135, -v149, v91 row_newbcast:5 row_mask:0xf bank_mask:0xf
	v_fmac_f32_dpp v136, -v149, v88 row_newbcast:2 row_mask:0xf bank_mask:0xf
	v_fmac_f32_dpp v137, -v149, v93 row_newbcast:7 row_mask:0xf bank_mask:0xf
	v_fmac_f32_dpp v3, -v149, v94 row_newbcast:8 row_mask:0xf bank_mask:0xf
	v_fmac_f32_dpp v135, -v149, v95 row_newbcast:9 row_mask:0xf bank_mask:0xf
	v_fmac_f32_dpp v136, -v149, v92 row_newbcast:6 row_mask:0xf bank_mask:0xf
	v_fmac_f32_dpp v137, -v149, v97 row_newbcast:11 row_mask:0xf bank_mask:0xf
	s_nop 0
	v_fmac_f32_dpp v136, -v149, v96 row_newbcast:10 row_mask:0xf bank_mask:0xf
	v_add_f32_e32 v20, v3, v135
	v_add_f32_e32 v21, v136, v137
	v_add_f32_e32 v71, v20, v21
	ds_read_b32 v148, v138 offset:512
	ds_read_b32 v149, v138 offset:576
	s_waitcnt lgkmcnt(4)
	v_mul_f32_dpp v132, -v144, v72 row_newbcast:2 row_mask:0xf bank_mask:0xf
	v_mul_f32_dpp v133, -v144, v73 row_newbcast:3 row_mask:0xf bank_mask:0xf
	v_fmac_f32_dpp v2, -v144, v74 row_newbcast:4 row_mask:0xf bank_mask:0xf
	v_mul_f32_dpp v131, -v144, v71 row_newbcast:1 row_mask:0xf bank_mask:0xf
	v_fmac_f32_dpp v132, -v144, v76 row_newbcast:6 row_mask:0xf bank_mask:0xf
	v_fmac_f32_dpp v133, -v144, v77 row_newbcast:7 row_mask:0xf bank_mask:0xf
	v_fmac_f32_dpp v2, -v144, v78 row_newbcast:8 row_mask:0xf bank_mask:0xf
	v_fmac_f32_dpp v131, -v144, v75 row_newbcast:5 row_mask:0xf bank_mask:0xf
	v_fmac_f32_dpp v132, -v144, v80 row_newbcast:10 row_mask:0xf bank_mask:0xf
	v_fmac_f32_dpp v133, -v144, v81 row_newbcast:11 row_mask:0xf bank_mask:0xf
	v_fmac_f32_dpp v2, -v144, v82 row_newbcast:12 row_mask:0xf bank_mask:0xf
	v_fmac_f32_dpp v131, -v144, v79 row_newbcast:9 row_mask:0xf bank_mask:0xf
	v_fmac_f32_dpp v132, -v144, v84 row_newbcast:14 row_mask:0xf bank_mask:0xf
	v_fmac_f32_dpp v133, -v144, v85 row_newbcast:15 row_mask:0xf bank_mask:0xf
	v_fmac_f32_dpp v2, -v145, v86 row_newbcast:0 row_mask:0xf bank_mask:0xf
	v_fmac_f32_dpp v131, -v144, v83 row_newbcast:13 row_mask:0xf bank_mask:0xf
	v_fmac_f32_dpp v132, -v145, v88 row_newbcast:2 row_mask:0xf bank_mask:0xf
	v_fmac_f32_dpp v133, -v145, v89 row_newbcast:3 row_mask:0xf bank_mask:0xf
	v_fmac_f32_dpp v2, -v145, v90 row_newbcast:4 row_mask:0xf bank_mask:0xf
	v_fmac_f32_dpp v131, -v145, v87 row_newbcast:1 row_mask:0xf bank_mask:0xf
	v_fmac_f32_dpp v132, -v145, v92 row_newbcast:6 row_mask:0xf bank_mask:0xf
	v_fmac_f32_dpp v133, -v145, v93 row_newbcast:7 row_mask:0xf bank_mask:0xf
	v_fmac_f32_dpp v2, -v145, v94 row_newbcast:8 row_mask:0xf bank_mask:0xf
	v_fmac_f32_dpp v131, -v145, v91 row_newbcast:5 row_mask:0xf bank_mask:0xf
	v_fmac_f32_dpp v132, -v145, v96 row_newbcast:10 row_mask:0xf bank_mask:0xf
	v_fmac_f32_dpp v133, -v145, v97 row_newbcast:11 row_mask:0xf bank_mask:0xf
	v_fmac_f32_dpp v131, -v145, v95 row_newbcast:9 row_mask:0xf bank_mask:0xf
	v_add_f32_e32 v20, v2, v131
	v_add_f32_e32 v21, v132, v133
	v_add_f32_e32 v70, v20, v21
	ds_read_b32 v144, v138 offset:256
	ds_read_b32 v145, v138 offset:320
	s_waitcnt lgkmcnt(4)
	v_mul_f32_dpp v135, -v140, v71 row_newbcast:1 row_mask:0xf bank_mask:0xf
	v_mul_f32_dpp v136, -v140, v72 row_newbcast:2 row_mask:0xf bank_mask:0xf
	v_mul_f32_dpp v137, -v140, v73 row_newbcast:3 row_mask:0xf bank_mask:0xf
	v_fmac_f32_dpp v163, -v140, v70 row_newbcast:0 row_mask:0xf bank_mask:0xf
	v_fmac_f32_dpp v135, -v140, v75 row_newbcast:5 row_mask:0xf bank_mask:0xf
	v_fmac_f32_dpp v136, -v140, v76 row_newbcast:6 row_mask:0xf bank_mask:0xf
	v_fmac_f32_dpp v137, -v140, v77 row_newbcast:7 row_mask:0xf bank_mask:0xf
	v_fmac_f32_dpp v163, -v140, v74 row_newbcast:4 row_mask:0xf bank_mask:0xf
	v_fmac_f32_dpp v135, -v140, v79 row_newbcast:9 row_mask:0xf bank_mask:0xf
	v_fmac_f32_dpp v136, -v140, v80 row_newbcast:10 row_mask:0xf bank_mask:0xf
	v_fmac_f32_dpp v137, -v140, v81 row_newbcast:11 row_mask:0xf bank_mask:0xf
	v_fmac_f32_dpp v163, -v140, v78 row_newbcast:8 row_mask:0xf bank_mask:0xf
	v_fmac_f32_dpp v135, -v140, v83 row_newbcast:13 row_mask:0xf bank_mask:0xf
	v_fmac_f32_dpp v136, -v140, v84 row_newbcast:14 row_mask:0xf bank_mask:0xf
	v_fmac_f32_dpp v137, -v140, v85 row_newbcast:15 row_mask:0xf bank_mask:0xf
	v_fmac_f32_dpp v163, -v140, v82 row_newbcast:12 row_mask:0xf bank_mask:0xf
	v_fmac_f32_dpp v135, -v141, v87 row_newbcast:1 row_mask:0xf bank_mask:0xf
	v_fmac_f32_dpp v136, -v141, v88 row_newbcast:2 row_mask:0xf bank_mask:0xf
	v_fmac_f32_dpp v137, -v141, v89 row_newbcast:3 row_mask:0xf bank_mask:0xf
	v_fmac_f32_dpp v163, -v141, v86 row_newbcast:0 row_mask:0xf bank_mask:0xf
	v_fmac_f32_dpp v135, -v141, v91 row_newbcast:5 row_mask:0xf bank_mask:0xf
	v_fmac_f32_dpp v136, -v141, v92 row_newbcast:6 row_mask:0xf bank_mask:0xf
	v_fmac_f32_dpp v137, -v141, v93 row_newbcast:7 row_mask:0xf bank_mask:0xf
	v_fmac_f32_dpp v163, -v141, v90 row_newbcast:4 row_mask:0xf bank_mask:0xf
	v_fmac_f32_dpp v135, -v141, v95 row_newbcast:9 row_mask:0xf bank_mask:0xf
	v_fmac_f32_dpp v136, -v141, v96 row_newbcast:10 row_mask:0xf bank_mask:0xf
	v_fmac_f32_dpp v137, -v141, v97 row_newbcast:11 row_mask:0xf bank_mask:0xf
	v_fmac_f32_dpp v163, -v141, v94 row_newbcast:8 row_mask:0xf bank_mask:0xf
	v_add_f32_e32 v20, v163, v135
	v_add_f32_e32 v21, v136, v137
	v_add_f32_e32 v69, v20, v21
	ds_read_b32 v140, v138 offset:0
	ds_read_b32 v141, v138 offset:64
	s_waitcnt lgkmcnt(4)
	v_fmac_f32_dpp v162, -v148, v70 row_newbcast:4 row_mask:0xf bank_mask:0xf
	v_mul_f32_dpp v131, -v148, v71 row_newbcast:5 row_mask:0xf bank_mask:0xf
	v_mul_f32_dpp v132, -v148, v72 row_newbcast:6 row_mask:0xf bank_mask:0xf
	v_mul_f32_dpp v133, -v148, v69 row_newbcast:3 row_mask:0xf bank_mask:0xf
	v_fmac_f32_dpp v162, -v148, v74 row_newbcast:8 row_mask:0xf bank_mask:0xf
	v_fmac_f32_dpp v131, -v148, v75 row_newbcast:9 row_mask:0xf bank_mask:0xf
	v_fmac_f32_dpp v132, -v148, v76 row_newbcast:10 row_mask:0xf bank_mask:0xf
	v_fmac_f32_dpp v133, -v148, v73 row_newbcast:7 row_mask:0xf bank_mask:0xf
	v_fmac_f32_dpp v162, -v148, v78 row_newbcast:12 row_mask:0xf bank_mask:0xf
	v_fmac_f32_dpp v131, -v148, v79 row_newbcast:13 row_mask:0xf bank_mask:0xf
	v_fmac_f32_dpp v132, -v148, v80 row_newbcast:14 row_mask:0xf bank_mask:0xf
	v_fmac_f32_dpp v133, -v148, v77 row_newbcast:11 row_mask:0xf bank_mask:0xf
	v_fmac_f32_dpp v162, -v149, v82 row_newbcast:0 row_mask:0xf bank_mask:0xf
	v_fmac_f32_dpp v131, -v149, v83 row_newbcast:1 row_mask:0xf bank_mask:0xf
	v_fmac_f32_dpp v132, -v149, v84 row_newbcast:2 row_mask:0xf bank_mask:0xf
	v_fmac_f32_dpp v133, -v148, v81 row_newbcast:15 row_mask:0xf bank_mask:0xf
	v_fmac_f32_dpp v162, -v149, v86 row_newbcast:4 row_mask:0xf bank_mask:0xf
	v_fmac_f32_dpp v131, -v149, v87 row_newbcast:5 row_mask:0xf bank_mask:0xf
	v_fmac_f32_dpp v132, -v149, v88 row_newbcast:6 row_mask:0xf bank_mask:0xf
	v_fmac_f32_dpp v133, -v149, v85 row_newbcast:3 row_mask:0xf bank_mask:0xf
	v_fmac_f32_dpp v162, -v149, v90 row_newbcast:8 row_mask:0xf bank_mask:0xf
	v_fmac_f32_dpp v131, -v149, v91 row_newbcast:9 row_mask:0xf bank_mask:0xf
	v_fmac_f32_dpp v132, -v149, v92 row_newbcast:10 row_mask:0xf bank_mask:0xf
	v_fmac_f32_dpp v133, -v149, v89 row_newbcast:7 row_mask:0xf bank_mask:0xf
	v_fmac_f32_dpp v162, -v149, v94 row_newbcast:12 row_mask:0xf bank_mask:0xf
	v_fmac_f32_dpp v131, -v149, v95 row_newbcast:13 row_mask:0xf bank_mask:0xf
	v_fmac_f32_dpp v132, -v149, v96 row_newbcast:14 row_mask:0xf bank_mask:0xf
	v_fmac_f32_dpp v133, -v149, v93 row_newbcast:11 row_mask:0xf bank_mask:0xf
	s_nop 1
	v_fmac_f32_dpp v133, -v149, v97 row_newbcast:15 row_mask:0xf bank_mask:0xf
	v_add_f32_e32 v20, v162, v131
	v_add_f32_e32 v21, v132, v133
	v_add_f32_e32 v68, v20, v21
	s_waitcnt lgkmcnt(2)
	v_mul_f32_dpp v137, -v144, v69 row_newbcast:3 row_mask:0xf bank_mask:0xf
	v_fmac_f32_dpp v161, -v144, v70 row_newbcast:4 row_mask:0xf bank_mask:0xf
	v_mul_f32_dpp v135, -v144, v71 row_newbcast:5 row_mask:0xf bank_mask:0xf
	v_mul_f32_dpp v136, -v144, v68 row_newbcast:2 row_mask:0xf bank_mask:0xf
	v_fmac_f32_dpp v137, -v144, v73 row_newbcast:7 row_mask:0xf bank_mask:0xf
	v_fmac_f32_dpp v161, -v144, v74 row_newbcast:8 row_mask:0xf bank_mask:0xf
	v_fmac_f32_dpp v135, -v144, v75 row_newbcast:9 row_mask:0xf bank_mask:0xf
	v_fmac_f32_dpp v136, -v144, v72 row_newbcast:6 row_mask:0xf bank_mask:0xf
	v_fmac_f32_dpp v137, -v144, v77 row_newbcast:11 row_mask:0xf bank_mask:0xf
	v_fmac_f32_dpp v161, -v144, v78 row_newbcast:12 row_mask:0xf bank_mask:0xf
	v_fmac_f32_dpp v135, -v144, v79 row_newbcast:13 row_mask:0xf bank_mask:0xf
	v_fmac_f32_dpp v136, -v144, v76 row_newbcast:10 row_mask:0xf bank_mask:0xf
	v_fmac_f32_dpp v137, -v144, v81 row_newbcast:15 row_mask:0xf bank_mask:0xf
	v_fmac_f32_dpp v161, -v145, v82 row_newbcast:0 row_mask:0xf bank_mask:0xf
	v_fmac_f32_dpp v135, -v145, v83 row_newbcast:1 row_mask:0xf bank_mask:0xf
	v_fmac_f32_dpp v136, -v144, v80 row_newbcast:14 row_mask:0xf bank_mask:0xf
	v_fmac_f32_dpp v137, -v145, v85 row_newbcast:3 row_mask:0xf bank_mask:0xf
	v_fmac_f32_dpp v161, -v145, v86 row_newbcast:4 row_mask:0xf bank_mask:0xf
	v_fmac_f32_dpp v135, -v145, v87 row_newbcast:5 row_mask:0xf bank_mask:0xf
	v_fmac_f32_dpp v136, -v145, v84 row_newbcast:2 row_mask:0xf bank_mask:0xf
	v_fmac_f32_dpp v137, -v145, v89 row_newbcast:7 row_mask:0xf bank_mask:0xf
	v_fmac_f32_dpp v161, -v145, v90 row_newbcast:8 row_mask:0xf bank_mask:0xf
	v_fmac_f32_dpp v135, -v145, v91 row_newbcast:9 row_mask:0xf bank_mask:0xf
	v_fmac_f32_dpp v136, -v145, v88 row_newbcast:6 row_mask:0xf bank_mask:0xf
	v_fmac_f32_dpp v137, -v145, v93 row_newbcast:11 row_mask:0xf bank_mask:0xf
	v_fmac_f32_dpp v161, -v145, v94 row_newbcast:12 row_mask:0xf bank_mask:0xf
	v_fmac_f32_dpp v135, -v145, v95 row_newbcast:13 row_mask:0xf bank_mask:0xf
	v_fmac_f32_dpp v136, -v145, v92 row_newbcast:10 row_mask:0xf bank_mask:0xf
	v_fmac_f32_dpp v137, -v145, v97 row_newbcast:15 row_mask:0xf bank_mask:0xf
	s_nop 0
	v_fmac_f32_dpp v136, -v145, v96 row_newbcast:14 row_mask:0xf bank_mask:0xf
	v_add_f32_e32 v20, v161, v135
	v_add_f32_e32 v21, v136, v137
	v_add_f32_e32 v67, v20, v21
	s_waitcnt lgkmcnt(0)
	v_mul_f32_dpp v132, -v140, v68 row_newbcast:2 row_mask:0xf bank_mask:0xf
	v_mul_f32_dpp v133, -v140, v69 row_newbcast:3 row_mask:0xf bank_mask:0xf
	v_fmac_f32_dpp v160, -v140, v70 row_newbcast:4 row_mask:0xf bank_mask:0xf
	v_mul_f32_dpp v131, -v140, v67 row_newbcast:1 row_mask:0xf bank_mask:0xf
	v_fmac_f32_dpp v132, -v140, v72 row_newbcast:6 row_mask:0xf bank_mask:0xf
	v_fmac_f32_dpp v133, -v140, v73 row_newbcast:7 row_mask:0xf bank_mask:0xf
	v_fmac_f32_dpp v160, -v140, v74 row_newbcast:8 row_mask:0xf bank_mask:0xf
	v_fmac_f32_dpp v131, -v140, v71 row_newbcast:5 row_mask:0xf bank_mask:0xf
	v_fmac_f32_dpp v132, -v140, v76 row_newbcast:10 row_mask:0xf bank_mask:0xf
	v_fmac_f32_dpp v133, -v140, v77 row_newbcast:11 row_mask:0xf bank_mask:0xf
	v_fmac_f32_dpp v160, -v140, v78 row_newbcast:12 row_mask:0xf bank_mask:0xf
	v_fmac_f32_dpp v131, -v140, v75 row_newbcast:9 row_mask:0xf bank_mask:0xf
	v_fmac_f32_dpp v132, -v140, v80 row_newbcast:14 row_mask:0xf bank_mask:0xf
	v_fmac_f32_dpp v133, -v140, v81 row_newbcast:15 row_mask:0xf bank_mask:0xf
	v_fmac_f32_dpp v160, -v141, v82 row_newbcast:0 row_mask:0xf bank_mask:0xf
	v_fmac_f32_dpp v131, -v140, v79 row_newbcast:13 row_mask:0xf bank_mask:0xf
	v_fmac_f32_dpp v132, -v141, v84 row_newbcast:2 row_mask:0xf bank_mask:0xf
	v_fmac_f32_dpp v133, -v141, v85 row_newbcast:3 row_mask:0xf bank_mask:0xf
	v_fmac_f32_dpp v160, -v141, v86 row_newbcast:4 row_mask:0xf bank_mask:0xf
	v_fmac_f32_dpp v131, -v141, v83 row_newbcast:1 row_mask:0xf bank_mask:0xf
	v_fmac_f32_dpp v132, -v141, v88 row_newbcast:6 row_mask:0xf bank_mask:0xf
	v_fmac_f32_dpp v133, -v141, v89 row_newbcast:7 row_mask:0xf bank_mask:0xf
	v_fmac_f32_dpp v160, -v141, v90 row_newbcast:8 row_mask:0xf bank_mask:0xf
	v_fmac_f32_dpp v131, -v141, v87 row_newbcast:5 row_mask:0xf bank_mask:0xf
	v_fmac_f32_dpp v132, -v141, v92 row_newbcast:10 row_mask:0xf bank_mask:0xf
	v_fmac_f32_dpp v133, -v141, v93 row_newbcast:11 row_mask:0xf bank_mask:0xf
	v_fmac_f32_dpp v160, -v141, v94 row_newbcast:12 row_mask:0xf bank_mask:0xf
	v_fmac_f32_dpp v131, -v141, v91 row_newbcast:9 row_mask:0xf bank_mask:0xf
	v_fmac_f32_dpp v132, -v141, v96 row_newbcast:14 row_mask:0xf bank_mask:0xf
	v_fmac_f32_dpp v133, -v141, v97 row_newbcast:15 row_mask:0xf bank_mask:0xf
	v_fmac_f32_dpp v131, -v141, v95 row_newbcast:13 row_mask:0xf bank_mask:0xf
	v_add_f32_e32 v20, v160, v131
	v_add_f32_e32 v21, v132, v133
	v_add_f32_e32 v66, v20, v21
	v_mov_b32_e32 v19, s5
	v_and_b32_e32 v20, 31, v1
	v_lshlrev_b32_e32 v20, 4, v20
	v_cmp_lt_u32_e32 vcc, 31, v1
	s_nop 1
	v_cndmask_b32_e32 v21, 0, v193, vcc
	v_or_b32_e32 v21, v21, v20
	v_add_u32_e32 v20, 0x1000, v20
	ds_read_b128 v[194:197], v19 offset:0
	ds_read_b128 v[198:201], v19 offset:32
	ds_read_b128 v[202:205], v19 offset:16
	ds_read_b128 v[206:209], v19 offset:48
	ds_read_b128 v[210:213], v19 offset:64
	ds_read_b128 v[214:217], v19 offset:96
	ds_read_b128 v[218:221], v19 offset:80
	ds_read_b128 v[222:225], v19 offset:112
	s_waitcnt lgkmcnt(6)
	v_pk_mul_f32 v[2:3], v[66:67], v[194:195]
	v_pk_mul_f32 v[4:5], v[68:69], v[196:197]
	v_pk_mul_f32 v[6:7], v[74:75], v[198:199]
	v_pk_mul_f32 v[8:9], v[76:77], v[200:201]
	v_cvt_pk_bf16_f32 v10, v2, v3
	v_cvt_pk_bf16_f32 v11, v4, v5
	v_cvt_pk_bf16_f32 v12, v6, v7
	v_cvt_pk_bf16_f32 v13, v8, v9
	global_store_dwordx4 v21, v[10:13], s[6:7] sc0 sc1
	s_waitcnt lgkmcnt(4)
	v_pk_mul_f32 v[2:3], v[70:71], v[202:203]
	v_pk_mul_f32 v[4:5], v[72:73], v[204:205]
	v_pk_mul_f32 v[6:7], v[78:79], v[206:207]
	v_pk_mul_f32 v[8:9], v[80:81], v[208:209]
	v_cvt_pk_bf16_f32 v14, v2, v3
	v_cvt_pk_bf16_f32 v15, v4, v5
	v_cvt_pk_bf16_f32 v16, v6, v7
	v_cvt_pk_bf16_f32 v17, v8, v9
	global_store_dwordx4 v21, v[14:17], s[6:7] offset:512 sc0 sc1
	s_waitcnt lgkmcnt(2)
	v_pk_mul_f32 v[2:3], v[82:83], v[210:211]
	v_pk_mul_f32 v[4:5], v[84:85], v[212:213]
	v_pk_mul_f32 v[6:7], v[90:91], v[214:215]
	v_pk_mul_f32 v[8:9], v[92:93], v[216:217]
	v_cvt_pk_bf16_f32 v10, v2, v3
	v_cvt_pk_bf16_f32 v11, v4, v5
	v_cvt_pk_bf16_f32 v12, v6, v7
	v_cvt_pk_bf16_f32 v13, v8, v9
	global_store_dwordx4 v21, v[10:13], s[6:7] offset:1024 sc0 sc1
	s_waitcnt lgkmcnt(0)
	v_pk_mul_f32 v[2:3], v[86:87], v[218:219]
	v_pk_mul_f32 v[4:5], v[88:89], v[220:221]
	v_pk_mul_f32 v[6:7], v[94:95], v[222:223]
	v_pk_mul_f32 v[8:9], v[96:97], v[224:225]
	v_cvt_pk_bf16_f32 v14, v2, v3
	v_cvt_pk_bf16_f32 v15, v4, v5
	v_cvt_pk_bf16_f32 v16, v6, v7
	v_cvt_pk_bf16_f32 v17, v8, v9
	global_store_dwordx4 v21, v[14:17], s[6:7] offset:1536 sc0 sc1
	s_and_saveexec_b64 s[0:1], vcc
	s_cbranch_execz .LBB0_655
	ds_read_b128 v[194:197], v19 offset:128
	ds_read_b128 v[198:201], v19 offset:160
	ds_read_b128 v[202:205], v19 offset:144
	ds_read_b128 v[206:209], v19 offset:176
	ds_read_b128 v[210:213], v19 offset:192
	ds_read_b128 v[214:217], v19 offset:224
	ds_read_b128 v[218:221], v19 offset:208
	ds_read_b128 v[222:225], v19 offset:240
	s_waitcnt lgkmcnt(6)
	v_pk_mul_f32 v[2:3], v[98:99], v[194:195]
	v_pk_mul_f32 v[4:5], v[100:101], v[196:197]
	v_pk_mul_f32 v[6:7], v[106:107], v[198:199]
	v_pk_mul_f32 v[8:9], v[108:109], v[200:201]
	v_cvt_pk_bf16_f32 v10, v2, v3
	v_cvt_pk_bf16_f32 v11, v4, v5
	v_cvt_pk_bf16_f32 v12, v6, v7
	v_cvt_pk_bf16_f32 v13, v8, v9
	global_store_dwordx4 v20, v[10:13], s[6:7] sc0 sc1
	s_waitcnt lgkmcnt(4)
	v_pk_mul_f32 v[2:3], v[102:103], v[202:203]
	v_pk_mul_f32 v[4:5], v[104:105], v[204:205]
	v_pk_mul_f32 v[6:7], v[110:111], v[206:207]
	v_pk_mul_f32 v[8:9], v[112:113], v[208:209]
	v_cvt_pk_bf16_f32 v14, v2, v3
	v_cvt_pk_bf16_f32 v15, v4, v5
	v_cvt_pk_bf16_f32 v16, v6, v7
	v_cvt_pk_bf16_f32 v17, v8, v9
	global_store_dwordx4 v20, v[14:17], s[6:7] offset:512 sc0 sc1
	s_waitcnt lgkmcnt(2)
	v_pk_mul_f32 v[2:3], v[114:115], v[210:211]
	v_pk_mul_f32 v[4:5], v[116:117], v[212:213]
	v_pk_mul_f32 v[6:7], v[122:123], v[214:215]
	v_pk_mul_f32 v[8:9], v[124:125], v[216:217]
	v_cvt_pk_bf16_f32 v10, v2, v3
	v_cvt_pk_bf16_f32 v11, v4, v5
	v_cvt_pk_bf16_f32 v12, v6, v7
	v_cvt_pk_bf16_f32 v13, v8, v9
	global_store_dwordx4 v20, v[10:13], s[6:7] offset:1024 sc0 sc1
	s_waitcnt lgkmcnt(0)
	v_pk_mul_f32 v[2:3], v[118:119], v[218:219]
	v_pk_mul_f32 v[4:5], v[120:121], v[220:221]
	v_pk_mul_f32 v[6:7], v[126:127], v[222:223]
	v_pk_mul_f32 v[8:9], v[128:129], v[224:225]
	v_cvt_pk_bf16_f32 v14, v2, v3
	v_cvt_pk_bf16_f32 v15, v4, v5
	v_cvt_pk_bf16_f32 v16, v6, v7
	v_cvt_pk_bf16_f32 v17, v8, v9
	global_store_dwordx4 v20, v[14:17], s[6:7] offset:1536 sc0 sc1
	s_nop 1
.LBB0_655:
	s_setprio 0
	s_or_b64 exec, exec, s[0:1]
	s_waitcnt vmcnt(0)
	s_barrier
	s_mov_b64 s[0:1], exec
	v_readlane_b32 s2, v249, 31
	v_readlane_b32 s3, v249, 32
	s_and_b64 s[2:3], s[0:1], s[2:3]
	v_readlane_b32 s81, v248, 18
	v_readlane_b32 s10, v248, 19
	v_readlane_b32 s8, v248, 21
	s_mov_b64 exec, s[2:3]
	s_cbranch_execz .LBB0_490
	v_readlane_b32 s2, v248, 26
	s_lshl_b32 s2, s2, 8
	s_lshl_b32 s3, s85, 2
	s_add_i32 s2, s2, s3
	s_ashr_i32 s3, s2, 31
	s_lshl_b64 s[2:3], s[2:3], 2
	v_readlane_b32 s4, v248, 14
	s_add_u32 s2, s4, s2
	v_readlane_b32 s4, v248, 15
	s_addc_u32 s3, s4, s3
	v_mov_b32_e32 v2, s84
	global_store_dword v2, v186, s[2:3] sc1
	s_branch .LBB0_490
